# stack: back-edge rotation of the six GEMM k-loops on top of the rstd-read hoist version
# speedup vs baseline: 1.0029x; 1.0011x over previous
; #define MFMA16(a, b, c) __builtin_amdgcn_mfma_f32_16x16x32_bf16((a), (b), (c), 0, 0, 0)
; DI bf16x8 ldfrag(const char* lds, int row, int chunk) { return *(const bf16x8*)(lds + swz(row, chunk)); }
; #define GEMM_SG1() do { __builtin_amdgcn_sched_group_barrier(0x100, 1, 0); __builtin_amdgcn_sched_group_barrier(0x008, 4, 0); } while (0)
; #define GEMM_SG2() do { __builtin_amdgcn_sched_group_barrier(0x100, 2, 0); __builtin_amdgcn_sched_group_barrier(0x008, 4, 0); } while (0)
; template <bool RSTD, bool SWAP>
; DI void gemm_tile(gacc_t& acc, const bf16_t* __restrict__ A, int lda, const bf16_t* __restrict__ Bt, int ldb, int K,
;                   char* lds, int tid, int wr, int wc, int lane, const float* ssq_row) {
;     ...
;     for (int kt = 0; kt < nk; ++kt) {
;         const char* cur = lds + (kt & 1) * 65536;
;         if (kt + 1 < nk) GEMM_ISSUE(kt + 1, (kt + 1) & 1);
;         bf16x8 bfr[2][4], afr[3];
; #pragma unroll
;         for (int n = 0; n < 4; ++n) bfr[0][n] = ldfrag(cur + 32768, wc * 64 + n * 16 + fr, fq);
;         afr[0] = ldfrag(cur, wr * 128 + fr, fq);
;         afr[1] = ldfrag(cur, wr * 128 + 16 + fr, fq);
; #pragma unroll
;         for (int idx = 0; idx < 16; ++idx) {
;             const int ks = idx >> 3, m = idx & 7;
;             if (idx < 14) afr[(idx + 2) % 3] = ldfrag(cur, wr * 128 + ((idx + 2) & 7) * 16 + fr, ((idx + 2) >> 3) * 4 + fq);
;             if (ks == 0 && m >= 2 && m < 6) bfr[1][m - 2] = ldfrag(cur + 32768, wc * 64 + (m - 2) * 16 + fr, 4 + fq);
; #pragma unroll
;             for (int n = 0; n < 4; ++n) acc[m][n] = SWAP ? MFMA16(bfr[ks][n], afr[idx % 3], acc[m][n]) : MFMA16(afr[idx % 3], bfr[ks][n], acc[m][n]);
;         }
;         __builtin_amdgcn_sched_group_barrier(0x100, 6, 0);
;     ...
;         GEMM_SG1(); GEMM_SG1(); GEMM_SG2(); GEMM_SG2(); GEMM_SG2(); GEMM_SG2(); GEMM_SG1(); GEMM_SG1();
;         GEMM_SG1(); GEMM_SG1(); GEMM_SG1(); GEMM_SG1(); GEMM_SG1(); GEMM_SG1();
;         __builtin_amdgcn_sched_group_barrier(0x008, 8, 0);
;         __builtin_amdgcn_sched_barrier(0);
;         asm volatile("s_waitcnt vmcnt(0)" ::: "memory");
;         __syncthreads();
.LBB0_373:
	s_and_b32 s20, s18, 0x10000
	v_lshl_add_u64 v[162:163], v[138:139], 0, s[6:7]
	s_add_i32 s20, s22, s20
	v_lshl_add_u64 v[164:165], v[136:137], 0, s[6:7]
	v_lshl_add_u64 v[166:167], v[162:163], 0, s[94:95]
	s_add_i32 s21, s20, 0x8000
	s_mov_b32 m0, s20
	v_lshl_add_u64 v[172:173], v[164:165], 0, s[14:15]
	global_load_lds_dwordx4 v[166:167], off
	v_mfma_f32_16x16x32_bf16 v[60:63], v[210:213], v[236:239], v[60:63]
	s_mov_b32 m0, s21
	v_lshl_add_u64 v[174:175], v[162:163], 0, s[96:97]
	global_load_lds_dwordx4 v[172:173], off
	v_mfma_f32_16x16x32_bf16 v[56:59], v[214:217], v[236:239], v[56:59]
	s_add_i32 m0, s20, 0x2000
	v_lshl_add_u64 v[176:177], v[164:165], 0, s[72:73]
	global_load_lds_dwordx4 v[174:175], off
	v_mfma_f32_16x16x32_bf16 v[52:55], v[218:221], v[236:239], v[52:55]
	s_add_i32 m0, s20, 0xa000
	v_lshl_add_u64 v[178:179], v[162:163], 0, s[80:81]
	global_load_lds_dwordx4 v[176:177], off
	v_mfma_f32_16x16x32_bf16 v[48:51], v[222:225], v[236:239], v[48:51]
	s_add_i32 m0, s20, 0x4000
	v_lshl_add_u64 v[180:181], v[164:165], 0, s[76:77]
	global_load_lds_dwordx4 v[178:179], off
	v_mfma_f32_16x16x32_bf16 v[44:47], v[210:213], v[240:243], v[44:47]
	s_add_i32 m0, s20, 0xc000
	v_lshl_add_u64 v[162:163], v[162:163], 0, s[82:83]
	global_load_lds_dwordx4 v[180:181], off
	v_mfma_f32_16x16x32_bf16 v[40:43], v[214:217], v[240:243], v[40:43]
	s_add_i32 m0, s20, 0x6000
	v_lshl_add_u64 v[164:165], v[164:165], 0, s[0:1]
	global_load_lds_dwordx4 v[162:163], off
	v_mfma_f32_16x16x32_bf16 v[36:39], v[218:221], v[240:243], v[36:39]
	s_add_i32 m0, s20, 0xe000
	s_add_i32 s19, s18, 0xffff0000
	global_load_lds_dwordx4 v[164:165], off
	v_mfma_f32_16x16x32_bf16 v[32:35], v[222:225], v[240:243], v[32:35]
	s_and_b32 s19, s19, 0x10000
	s_add_i32 s19, s19, 0
	v_add_u32_e32 v146, s19, v144
	v_add3_u32 v166, v146, v150, v151
	ds_read_b128 v[162:165], v166 offset:32768
	ds_read_b128 v[186:189], v166 offset:34816
	ds_read_b128 v[194:197], v166 offset:36864
	ds_read_b128 v[198:201], v166 offset:38912
	v_add_u32_e32 v167, v146, v148
	ds_read_b128 v[190:193], v167
	ds_read_b128 v[202:205], v167 offset:2048
	v_add_u32_e32 v166, v146, v152
	ds_read_b128 v[206:209], v167 offset:4096
	v_mfma_f32_16x16x32_bf16 v[28:31], v[210:213], v[244:247], v[28:31]
	v_mfma_f32_16x16x32_bf16 v[24:27], v[214:217], v[244:247], v[24:27]
	v_mfma_f32_16x16x32_bf16 v[20:23], v[218:221], v[244:247], v[20:23]
	v_mfma_f32_16x16x32_bf16 v[16:19], v[222:225], v[244:247], v[16:19]
	v_mfma_f32_16x16x32_bf16 v[12:15], v[210:213], v[248:251], v[12:15]
	v_mfma_f32_16x16x32_bf16 v[8:11], v[214:217], v[248:251], v[8:11]
	v_mfma_f32_16x16x32_bf16 v[4:7], v[218:221], v[248:251], v[4:7]
	v_mfma_f32_16x16x32_bf16 v[0:3], v[222:225], v[248:251], v[0:3]
	s_waitcnt lgkmcnt(2)
	v_mfma_f32_16x16x32_bf16 v[124:127], v[162:165], v[190:193], v[124:127]
	v_add_u32_e32 v146, v146, v154
	v_mfma_f32_16x16x32_bf16 v[120:123], v[186:189], v[190:193], v[120:123]
	v_mfma_f32_16x16x32_bf16 v[116:119], v[194:197], v[190:193], v[116:119]
	v_mfma_f32_16x16x32_bf16 v[112:115], v[198:201], v[190:193], v[112:115]
	ds_read_b128 v[190:193], v166
	v_add_u32_e32 v166, s19, v149
	v_add_u32_e32 v172, v166, v153
	s_waitcnt lgkmcnt(2)
	v_mfma_f32_16x16x32_bf16 v[108:111], v[162:165], v[202:205], v[108:111]
	v_mfma_f32_16x16x32_bf16 v[104:107], v[186:189], v[202:205], v[104:107]
	v_mfma_f32_16x16x32_bf16 v[100:103], v[194:197], v[202:205], v[100:103]
	v_mfma_f32_16x16x32_bf16 v[96:99], v[198:201], v[202:205], v[96:99]
	ds_read_b128 v[202:205], v167 offset:8192
	ds_read_b128 v[210:213], v172 offset:32768
	s_waitcnt lgkmcnt(3)
	v_mfma_f32_16x16x32_bf16 v[92:95], v[162:165], v[206:209], v[92:95]
	v_mfma_f32_16x16x32_bf16 v[88:91], v[186:189], v[206:209], v[88:91]
	v_mfma_f32_16x16x32_bf16 v[84:87], v[194:197], v[206:209], v[84:87]
	v_mfma_f32_16x16x32_bf16 v[80:83], v[198:201], v[206:209], v[80:83]
	ds_read_b128 v[206:209], v167 offset:10240
	ds_read_b128 v[214:217], v172 offset:34816
	s_waitcnt lgkmcnt(4)
	v_mfma_f32_16x16x32_bf16 v[76:79], v[162:165], v[190:193], v[76:79]
	v_mfma_f32_16x16x32_bf16 v[72:75], v[186:189], v[190:193], v[72:75]
	v_mfma_f32_16x16x32_bf16 v[68:71], v[194:197], v[190:193], v[68:71]
	v_mfma_f32_16x16x32_bf16 v[64:67], v[198:201], v[190:193], v[64:67]
	ds_read_b128 v[190:193], v167 offset:12288
	v_add_u32_e32 v167, v166, v155
	ds_read_b128 v[218:221], v172 offset:36864
	s_waitcnt lgkmcnt(5)
	v_mfma_f32_16x16x32_bf16 v[60:63], v[162:165], v[202:205], v[60:63]
	v_mfma_f32_16x16x32_bf16 v[56:59], v[186:189], v[202:205], v[56:59]
	v_mfma_f32_16x16x32_bf16 v[52:55], v[194:197], v[202:205], v[52:55]
	v_mfma_f32_16x16x32_bf16 v[48:51], v[198:201], v[202:205], v[48:51]
	ds_read_b128 v[222:225], v167 offset:38912
	ds_read_b128 v[202:205], v146
	v_add_u32_e32 v146, v166, v148
	s_waitcnt lgkmcnt(5)
	v_mfma_f32_16x16x32_bf16 v[44:47], v[162:165], v[206:209], v[44:47]
	v_add_u32_e32 v167, v166, v152
	v_mfma_f32_16x16x32_bf16 v[40:43], v[186:189], v[206:209], v[40:43]
	v_mfma_f32_16x16x32_bf16 v[36:39], v[194:197], v[206:209], v[36:39]
	v_mfma_f32_16x16x32_bf16 v[32:35], v[198:201], v[206:209], v[32:35]
	ds_read_b128 v[206:209], v146
	s_waitcnt lgkmcnt(4)
	v_mfma_f32_16x16x32_bf16 v[28:31], v[162:165], v[190:193], v[28:31]
	v_mfma_f32_16x16x32_bf16 v[24:27], v[186:189], v[190:193], v[24:27]
	v_mfma_f32_16x16x32_bf16 v[20:23], v[194:197], v[190:193], v[20:23]
	v_mfma_f32_16x16x32_bf16 v[16:19], v[198:201], v[190:193], v[16:19]
	ds_read_b128 v[190:193], v146 offset:2048
	s_waitcnt lgkmcnt(2)
; #define MFMA16(a, b, c) __builtin_amdgcn_mfma_f32_16x16x32_bf16((a), (b), (c), 0, 0, 0)
; DI bf16x8 ldfrag(const char* lds, int row, int chunk) { return *(const bf16x8*)(lds + swz(row, chunk)); }
; #define GEMM_SG1() do { __builtin_amdgcn_sched_group_barrier(0x100, 1, 0); __builtin_amdgcn_sched_group_barrier(0x008, 4, 0); } while (0)
; #define GEMM_SG2() do { __builtin_amdgcn_sched_group_barrier(0x100, 2, 0); __builtin_amdgcn_sched_group_barrier(0x008, 4, 0); } while (0)
; template <bool RSTD, bool SWAP>
; DI void gemm_tile(gacc_t& acc, const bf16_t* __restrict__ A, int lda, const bf16_t* __restrict__ Bt, int ldb, int K,
;                   char* lds, int tid, int wr, int wc, int lane, const float* ssq_row) {
;     ...
;     for (int kt = 0; kt < nk; ++kt) {
;         const char* cur = lds + (kt & 1) * 65536;
;         if (kt + 1 < nk) GEMM_ISSUE(kt + 1, (kt + 1) & 1);
;         bf16x8 bfr[2][4], afr[3];
; #pragma unroll
;         for (int n = 0; n < 4; ++n) bfr[0][n] = ldfrag(cur + 32768, wc * 64 + n * 16 + fr, fq);
;         afr[0] = ldfrag(cur, wr * 128 + fr, fq);
;         afr[1] = ldfrag(cur, wr * 128 + 16 + fr, fq);
; #pragma unroll
;         for (int idx = 0; idx < 16; ++idx) {
;             const int ks = idx >> 3, m = idx & 7;
;             if (idx < 14) afr[(idx + 2) % 3] = ldfrag(cur, wr * 128 + ((idx + 2) & 7) * 16 + fr, ((idx + 2) >> 3) * 4 + fq);
;             if (ks == 0 && m >= 2 && m < 6) bfr[1][m - 2] = ldfrag(cur + 32768, wc * 64 + (m - 2) * 16 + fr, 4 + fq);
; #pragma unroll
;             for (int n = 0; n < 4; ++n) acc[m][n] = SWAP ? MFMA16(bfr[ks][n], afr[idx % 3], acc[m][n]) : MFMA16(afr[idx % 3], bfr[ks][n], acc[m][n]);
;         }
;         __builtin_amdgcn_sched_group_barrier(0x100, 6, 0);
;     ...
;         GEMM_SG1(); GEMM_SG1(); GEMM_SG2(); GEMM_SG2(); GEMM_SG2(); GEMM_SG2(); GEMM_SG1(); GEMM_SG1();
;         GEMM_SG1(); GEMM_SG1(); GEMM_SG1(); GEMM_SG1(); GEMM_SG1(); GEMM_SG1();
;         __builtin_amdgcn_sched_group_barrier(0x008, 8, 0);
;         __builtin_amdgcn_sched_barrier(0);
;         asm volatile("s_waitcnt vmcnt(0)" ::: "memory");
;         __syncthreads();
	v_mfma_f32_16x16x32_bf16 v[12:15], v[162:165], v[202:205], v[12:15]
	v_mfma_f32_16x16x32_bf16 v[8:11], v[186:189], v[202:205], v[8:11]
	v_mfma_f32_16x16x32_bf16 v[4:7], v[194:197], v[202:205], v[4:7]
	v_mfma_f32_16x16x32_bf16 v[0:3], v[198:201], v[202:205], v[0:3]
	ds_read_b128 v[162:165], v146 offset:4096
	s_waitcnt lgkmcnt(2)
	v_mfma_f32_16x16x32_bf16 v[124:127], v[210:213], v[206:209], v[124:127]
	v_mfma_f32_16x16x32_bf16 v[120:123], v[214:217], v[206:209], v[120:123]
	v_mfma_f32_16x16x32_bf16 v[116:119], v[218:221], v[206:209], v[116:119]
	v_mfma_f32_16x16x32_bf16 v[112:115], v[222:225], v[206:209], v[112:115]
	ds_read_b128 v[186:189], v167
	s_waitcnt lgkmcnt(2)
	v_mfma_f32_16x16x32_bf16 v[108:111], v[210:213], v[190:193], v[108:111]
	v_mfma_f32_16x16x32_bf16 v[104:107], v[214:217], v[190:193], v[104:107]
	v_mfma_f32_16x16x32_bf16 v[100:103], v[218:221], v[190:193], v[100:103]
	v_mfma_f32_16x16x32_bf16 v[96:99], v[222:225], v[190:193], v[96:99]
	ds_read_b128 v[236:239], v146 offset:8192
	s_waitcnt lgkmcnt(2)
	v_mfma_f32_16x16x32_bf16 v[92:95], v[210:213], v[162:165], v[92:95]
	v_mfma_f32_16x16x32_bf16 v[88:91], v[214:217], v[162:165], v[88:91]
	v_mfma_f32_16x16x32_bf16 v[84:87], v[218:221], v[162:165], v[84:87]
	v_mfma_f32_16x16x32_bf16 v[80:83], v[222:225], v[162:165], v[80:83]
	ds_read_b128 v[240:243], v146 offset:10240
	ds_read_b128 v[244:247], v146 offset:12288
	v_add_u32_e32 v146, v166, v154
	ds_read_b128 v[248:251], v146
	s_waitcnt lgkmcnt(4)
	v_mfma_f32_16x16x32_bf16 v[76:79], v[210:213], v[186:189], v[76:79]
	v_mfma_f32_16x16x32_bf16 v[72:75], v[214:217], v[186:189], v[72:75]
	v_mfma_f32_16x16x32_bf16 v[68:71], v[218:221], v[186:189], v[68:71]
	v_mfma_f32_16x16x32_bf16 v[64:67], v[222:225], v[186:189], v[64:67]
	s_waitcnt lgkmcnt(0)
	s_waitcnt vmcnt(0)
	s_add_u32 s6, s6, 0x80
	s_addc_u32 s7, s7, 0
	s_add_i32 s18, s18, 0x10000
	s_cmpk_lg_i32 s6, 0x780
	s_waitcnt vmcnt(0)
	s_cbranch_scc1 .Lkhead_373
	s_barrier
	v_mfma_f32_16x16x32_bf16 v[60:63], v[210:213], v[236:239], v[60:63]
	v_mfma_f32_16x16x32_bf16 v[56:59], v[214:217], v[236:239], v[56:59]
	v_mfma_f32_16x16x32_bf16 v[52:55], v[218:221], v[236:239], v[52:55]
	v_mfma_f32_16x16x32_bf16 v[48:51], v[222:225], v[236:239], v[48:51]
	v_mfma_f32_16x16x32_bf16 v[44:47], v[210:213], v[240:243], v[44:47]
	v_mfma_f32_16x16x32_bf16 v[40:43], v[214:217], v[240:243], v[40:43]
	v_mfma_f32_16x16x32_bf16 v[36:39], v[218:221], v[240:243], v[36:39]
	v_mfma_f32_16x16x32_bf16 v[32:35], v[222:225], v[240:243], v[32:35]
	v_mfma_f32_16x16x32_bf16 v[28:31], v[210:213], v[244:247], v[28:31]
	v_mfma_f32_16x16x32_bf16 v[24:27], v[214:217], v[244:247], v[24:27]
	v_mfma_f32_16x16x32_bf16 v[20:23], v[218:221], v[244:247], v[20:23]
	v_mfma_f32_16x16x32_bf16 v[16:19], v[222:225], v[244:247], v[16:19]
	v_mfma_f32_16x16x32_bf16 v[12:15], v[210:213], v[248:251], v[12:15]
	v_mfma_f32_16x16x32_bf16 v[8:11], v[214:217], v[248:251], v[8:11]
	v_mfma_f32_16x16x32_bf16 v[4:7], v[218:221], v[248:251], v[4:7]
	v_mfma_f32_16x16x32_bf16 v[0:3], v[222:225], v[248:251], v[0:3]
	ds_read_b128 v[136:139], v161
	ds_read_b128 v[162:165], v161 offset:2048
	ds_read_b128 v[190:193], v161 offset:4096
	ds_read_b128 v[194:197], v161 offset:6144
	v_add_u32_e32 v146, v156, v148
	ds_read_b128 v[186:189], v146
	ds_read_b128 v[198:201], v146 offset:2048
	v_add_u32_e32 v166, v156, v152
	ds_read_b128 v[202:205], v146 offset:4096
	s_waitcnt lgkmcnt(2)
	v_mfma_f32_16x16x32_bf16 v[124:127], v[136:139], v[186:189], v[124:127]
	s_sext_i32_i8 s6, s16
	v_mfma_f32_16x16x32_bf16 v[120:123], v[162:165], v[186:189], v[120:123]
	v_mfma_f32_16x16x32_bf16 v[116:119], v[190:193], v[186:189], v[116:119]
	v_mfma_f32_16x16x32_bf16 v[112:115], v[194:197], v[186:189], v[112:115]
	ds_read_b128 v[186:189], v166
	v_add_u32_e32 v166, v157, v153
	s_waitcnt lgkmcnt(2)
	v_mfma_f32_16x16x32_bf16 v[108:111], v[136:139], v[198:201], v[108:111]
	v_mfma_f32_16x16x32_bf16 v[104:107], v[162:165], v[198:201], v[104:107]
	v_mfma_f32_16x16x32_bf16 v[100:103], v[190:193], v[198:201], v[100:103]
	v_mfma_f32_16x16x32_bf16 v[96:99], v[194:197], v[198:201], v[96:99]
	ds_read_b128 v[198:201], v146 offset:8192
	ds_read_b128 v[206:209], v166
	s_waitcnt lgkmcnt(3)
	v_mfma_f32_16x16x32_bf16 v[92:95], v[136:139], v[202:205], v[92:95]
	v_mfma_f32_16x16x32_bf16 v[88:91], v[162:165], v[202:205], v[88:91]
	v_mfma_f32_16x16x32_bf16 v[84:87], v[190:193], v[202:205], v[84:87]
	v_mfma_f32_16x16x32_bf16 v[80:83], v[194:197], v[202:205], v[80:83]
	ds_read_b128 v[202:205], v146 offset:10240
	ds_read_b128 v[210:213], v166 offset:2048
	s_waitcnt lgkmcnt(4)
	v_mfma_f32_16x16x32_bf16 v[76:79], v[136:139], v[186:189], v[76:79]
	v_mfma_f32_16x16x32_bf16 v[72:75], v[162:165], v[186:189], v[72:75]
	v_mfma_f32_16x16x32_bf16 v[68:71], v[190:193], v[186:189], v[68:71]
	v_mfma_f32_16x16x32_bf16 v[64:67], v[194:197], v[186:189], v[64:67]
	ds_read_b128 v[186:189], v146 offset:12288
	v_add_u32_e32 v146, v156, v154
	ds_read_b128 v[214:217], v166 offset:4096
	s_waitcnt lgkmcnt(5)
	v_mfma_f32_16x16x32_bf16 v[60:63], v[136:139], v[198:201], v[60:63]
	v_mfma_f32_16x16x32_bf16 v[56:59], v[162:165], v[198:201], v[56:59]
	v_mfma_f32_16x16x32_bf16 v[52:55], v[190:193], v[198:201], v[52:55]
	v_mfma_f32_16x16x32_bf16 v[48:51], v[194:197], v[198:201], v[48:51]
	ds_read_b128 v[198:201], v146
	v_add_u32_e32 v146, v157, v155
	ds_read_b128 v[218:221], v146 offset:6144
	v_add_u32_e32 v146, v158, v148
	s_waitcnt lgkmcnt(5)
	v_mfma_f32_16x16x32_bf16 v[44:47], v[136:139], v[202:205], v[44:47]
	v_mfma_f32_16x16x32_bf16 v[40:43], v[162:165], v[202:205], v[40:43]
	v_mfma_f32_16x16x32_bf16 v[36:39], v[190:193], v[202:205], v[36:39]
	v_mfma_f32_16x16x32_bf16 v[32:35], v[194:197], v[202:205], v[32:35]
	ds_read_b128 v[202:205], v146
	s_waitcnt lgkmcnt(4)
; #define MFMA16(a, b, c) __builtin_amdgcn_mfma_f32_16x16x32_bf16((a), (b), (c), 0, 0, 0)
; DI bf16x8 ldfrag(const char* lds, int row, int chunk) { return *(const bf16x8*)(lds + swz(row, chunk)); }
; template <bool RSTD, bool SWAP>
; DI void gemm_tile(gacc_t& acc, const bf16_t* __restrict__ A, int lda, const bf16_t* __restrict__ Bt, int ldb, int K,
;                   char* lds, int tid, int wr, int wc, int lane, const float* ssq_row) {
;     ...
;         for (int idx = 0; idx < 16; ++idx) {
;             const int ks = idx >> 3, m = idx & 7;
;             if (idx < 14) afr[(idx + 2) % 3] = ldfrag(cur, wr * 128 + ((idx + 2) & 7) * 16 + fr, ((idx + 2) >> 3) * 4 + fq);
;             if (ks == 0 && m >= 2 && m < 6) bfr[1][m - 2] = ldfrag(cur + 32768, wc * 64 + (m - 2) * 16 + fr, 4 + fq);
; #pragma unroll
;             for (int n = 0; n < 4; ++n) acc[m][n] = SWAP ? MFMA16(bfr[ks][n], afr[idx % 3], acc[m][n]) : MFMA16(afr[idx % 3], bfr[ks][n], acc[m][n]);
;     DI void operator()(gacc_t& acc, int pm, int pn, char* lds, int tid, int wr, int wc, int lane) const {
;     ...
;         const int fr = lane & 15, fq = lane >> 4;
;         char* lbase = lds + (wr * 128 + fr) * 528 + (wc * 64 + 4 * fq) * 2;
;         const float* rl = (const float*)(lds + RSTD_OFF) + wr * 128 + fr;
; #pragma unroll
;         for (int m = 0; m < 8; ++m) {
;             const float r = rl[m * 16];
; #pragma unroll
;             for (int n = 0; n < 4; ++n) {
;                 float g[4];
; #pragma unroll
;                 for (int j = 0; j < 4; ++j) {
;                     const float x = acc[m][n][j] * r;
;                     const float u = 0.7978845608028654f * (x + 0.044715f * x * x * x);
;                     const float e = __builtin_amdgcn_exp2f(-2.885390081777927f * u);
;                     g[j] = x * __builtin_amdgcn_rcpf(1.0f + e);
;                 }
	v_mfma_f32_16x16x32_bf16 v[28:31], v[136:139], v[186:189], v[28:31]
	v_mfma_f32_16x16x32_bf16 v[24:27], v[162:165], v[186:189], v[24:27]
	v_mfma_f32_16x16x32_bf16 v[20:23], v[190:193], v[186:189], v[20:23]
	v_mfma_f32_16x16x32_bf16 v[16:19], v[194:197], v[186:189], v[16:19]
	ds_read_b128 v[186:189], v146 offset:2048
	s_waitcnt lgkmcnt(3)
	v_mfma_f32_16x16x32_bf16 v[12:15], v[136:139], v[198:201], v[12:15]
	v_mfma_f32_16x16x32_bf16 v[8:11], v[162:165], v[198:201], v[8:11]
	v_mfma_f32_16x16x32_bf16 v[4:7], v[190:193], v[198:201], v[4:7]
	v_mfma_f32_16x16x32_bf16 v[0:3], v[194:197], v[198:201], v[0:3]
	ds_read_b128 v[136:139], v146 offset:4096
	s_waitcnt lgkmcnt(2)
	v_mfma_f32_16x16x32_bf16 v[162:165], v[206:209], v[202:205], v[124:127]
	s_nop 2
	v_add_u32_e32 v124, v158, v152
	v_mfma_f32_16x16x32_bf16 v[120:123], v[210:213], v[202:205], v[120:123]
	v_mfma_f32_16x16x32_bf16 v[116:119], v[214:217], v[202:205], v[116:119]
	v_mfma_f32_16x16x32_bf16 v[112:115], v[218:221], v[202:205], v[112:115]
	ds_read_b128 v[124:127], v124
	s_waitcnt lgkmcnt(2)
	v_mfma_f32_16x16x32_bf16 v[108:111], v[206:209], v[186:189], v[108:111]
	v_mfma_f32_16x16x32_bf16 v[104:107], v[210:213], v[186:189], v[104:107]
	v_mfma_f32_16x16x32_bf16 v[100:103], v[214:217], v[186:189], v[100:103]
	v_mfma_f32_16x16x32_bf16 v[96:99], v[218:221], v[186:189], v[96:99]
	ds_read_b128 v[186:189], v146 offset:8192
	s_waitcnt lgkmcnt(2)
	v_mfma_f32_16x16x32_bf16 v[92:95], v[206:209], v[136:139], v[92:95]
	v_mfma_f32_16x16x32_bf16 v[88:91], v[210:213], v[136:139], v[88:91]
	v_mfma_f32_16x16x32_bf16 v[84:87], v[214:217], v[136:139], v[84:87]
	v_mfma_f32_16x16x32_bf16 v[80:83], v[218:221], v[136:139], v[80:83]
	ds_read_b128 v[136:139], v146 offset:10240
	s_waitcnt lgkmcnt(2)
	v_mfma_f32_16x16x32_bf16 v[76:79], v[206:209], v[124:127], v[76:79]
	v_mfma_f32_16x16x32_bf16 v[72:75], v[210:213], v[124:127], v[72:75]
	v_mfma_f32_16x16x32_bf16 v[68:71], v[214:217], v[124:127], v[68:71]
	v_mfma_f32_16x16x32_bf16 v[64:67], v[218:221], v[124:127], v[64:67]
	ds_read_b128 v[124:127], v146 offset:12288
	v_add_u32_e32 v146, v158, v154
	s_waitcnt lgkmcnt(2)
	v_mfma_f32_16x16x32_bf16 v[60:63], v[206:209], v[186:189], v[60:63]
	v_mfma_f32_16x16x32_bf16 v[56:59], v[210:213], v[186:189], v[56:59]
	v_mfma_f32_16x16x32_bf16 v[52:55], v[214:217], v[186:189], v[52:55]
	v_mfma_f32_16x16x32_bf16 v[48:51], v[218:221], v[186:189], v[48:51]
	ds_read_b128 v[186:189], v146
	s_waitcnt lgkmcnt(2)
	v_mfma_f32_16x16x32_bf16 v[44:47], v[206:209], v[136:139], v[44:47]
	v_mfma_f32_16x16x32_bf16 v[40:43], v[210:213], v[136:139], v[40:43]
	v_mfma_f32_16x16x32_bf16 v[36:39], v[214:217], v[136:139], v[36:39]
	v_mfma_f32_16x16x32_bf16 v[32:35], v[218:221], v[136:139], v[32:35]
	s_waitcnt lgkmcnt(1)
	v_mfma_f32_16x16x32_bf16 v[28:31], v[206:209], v[124:127], v[28:31]
	v_mfma_f32_16x16x32_bf16 v[24:27], v[210:213], v[124:127], v[24:27]
	v_mfma_f32_16x16x32_bf16 v[20:23], v[214:217], v[124:127], v[20:23]
	v_mfma_f32_16x16x32_bf16 v[16:19], v[218:221], v[124:127], v[16:19]
	s_waitcnt lgkmcnt(0)
	v_mfma_f32_16x16x32_bf16 v[12:15], v[206:209], v[186:189], v[12:15]
	v_mfma_f32_16x16x32_bf16 v[8:11], v[210:213], v[186:189], v[8:11]
	v_mfma_f32_16x16x32_bf16 v[4:7], v[214:217], v[186:189], v[4:7]
	v_mfma_f32_16x16x32_bf16 v[0:3], v[218:221], v[186:189], v[0:3]
	v_mov_b32_e32 v124, v141
	v_mov_b32_e32 v125, v140
	s_waitcnt vmcnt(0)
	s_barrier
	s_nop 0
	v_and_b32_e32 v127, 15, v124
	v_or_b32_e32 v126, v127, v145
	v_ashrrev_i32_e32 v124, 1, v124
	v_mul_lo_u32 v126, v126, s3
	v_and_b32_e32 v124, -8, v124
	v_lshl_add_u32 v127, v127, 2, v160
	v_add3_u32 v126, v159, v126, v124
	ds_read_b32 v244, v127
	ds_read_b32 v245, v127 offset:64
	ds_read_b32 v246, v127 offset:128
	ds_read_b32 v247, v127 offset:192
	ds_read_b32 v248, v127 offset:256
	ds_read_b32 v249, v127 offset:320
	ds_read_b32 v250, v127 offset:384
	ds_read_b32 v251, v127 offset:448
	s_waitcnt lgkmcnt(0)
	v_mov_b32_e32 v124, v244
	v_pk_mul_f32 v[136:137], v[162:163], v[124:125] op_sel_hi:[1,0]
	s_nop 0
	v_mul_f32_e32 v138, 0x3d372713, v136
	v_mul_f32_e32 v139, 0x3d372713, v137
	v_mul_f32_e32 v138, v136, v138
	v_mul_f32_e32 v139, v137, v139
	v_fma_f32 v138, v136, v138, v136
	v_fma_f32 v139, v137, v139, v137
	v_mul_f32_e32 v138, 0x3f4c422a, v138
	v_mul_f32_e32 v139, 0x3f4c422a, v139
	v_mul_f32_e32 v138, 0xc038aa3b, v138
	v_mul_f32_e32 v139, 0xc038aa3b, v139
	v_exp_f32_e32 v138, v138
	v_exp_f32_e32 v139, v139
	v_pk_mul_f32 v[120:121], v[120:121], v[124:125] op_sel_hi:[1,0]
	v_pk_mul_f32 v[122:123], v[122:123], v[124:125] op_sel_hi:[1,0]
	v_add_f32_e32 v138, 1.0, v138
	v_add_f32_e32 v139, 1.0, v139
	v_rcp_f32_e32 v138, v138
	v_rcp_f32_e32 v139, v139
	v_pk_mul_f32 v[116:117], v[116:117], v[124:125] op_sel_hi:[1,0]
	v_pk_mul_f32 v[118:119], v[118:119], v[124:125] op_sel_hi:[1,0]
	v_pk_mul_f32 v[112:113], v[112:113], v[124:125] op_sel_hi:[1,0]
	v_pk_mul_f32 v[136:137], v[136:137], v[138:139]
	v_pk_mul_f32 v[138:139], v[164:165], v[124:125] op_sel_hi:[1,0]
	v_cvt_pk_bf16_f32 v136, v136, v137
	v_mul_f32_e32 v146, 0x3d372713, v138
	v_mul_f32_e32 v146, v138, v146
	v_fma_f32 v146, v138, v146, v138
	v_mul_f32_e32 v146, 0x3f4c422a, v146
	v_mul_f32_e32 v146, 0xc038aa3b, v146
	v_exp_f32_e32 v146, v146
	v_pk_mul_f32 v[114:115], v[114:115], v[124:125] op_sel_hi:[1,0]
	v_add_f32_e32 v146, 1.0, v146
	v_rcp_f32_e32 v162, v146
	v_mul_f32_e32 v146, 0x3d372713, v139
	v_mul_f32_e32 v146, v139, v146
	v_fma_f32 v146, v139, v146, v139
	v_mul_f32_e32 v146, 0x3f4c422a, v146
	v_mul_f32_e32 v146, 0xc038aa3b, v146
	v_exp_f32_e32 v146, v146
	s_nop 0
	v_add_f32_e32 v146, 1.0, v146
	v_rcp_f32_e32 v163, v146
	s_nop 0
; DI unsigned pk2(float a, float b) { f32x2 v = {a, b}; bf16x2_t r = __builtin_convertvector(v, bf16x2_t); return __builtin_bit_cast(unsigned, r); }
;     DI void operator()(gacc_t& acc, int pm, int pn, char* lds, int tid, int wr, int wc, int lane) const {
;     ...
;         for (int m = 0; m < 8; ++m) {
;             const float r = rl[m * 16];
; #pragma unroll
;             for (int n = 0; n < 4; ++n) {
;                 float g[4];
; #pragma unroll
;                 for (int j = 0; j < 4; ++j) {
;                     const float x = acc[m][n][j] * r;
;                     const float u = 0.7978845608028654f * (x + 0.044715f * x * x * x);
;                     const float e = __builtin_amdgcn_exp2f(-2.885390081777927f * u);
;                     g[j] = x * __builtin_amdgcn_rcpf(1.0f + e);
;                 }
;                 u32x2 w; w.x = pk2(g[0], g[1]); w.y = pk2(g[2], g[3]);
;                 *(u32x2*)(lbase + m * 16 * 528 + n * 32) = w;
;             }
;             __builtin_amdgcn_sched_barrier(0);
	v_pk_mul_f32 v[138:139], v[138:139], v[162:163]
	s_nop 0
	v_cvt_pk_bf16_f32 v137, v138, v139
	v_mul_f32_e32 v138, 0x3d372713, v120
	v_mul_f32_e32 v139, 0x3d372713, v121
	v_mul_f32_e32 v138, v120, v138
	v_mul_f32_e32 v139, v121, v139
	v_fma_f32 v138, v120, v138, v120
	v_fma_f32 v139, v121, v139, v121
	v_mul_f32_e32 v138, 0x3f4c422a, v138
	v_mul_f32_e32 v139, 0x3f4c422a, v139
	v_mul_f32_e32 v138, 0xc038aa3b, v138
	v_mul_f32_e32 v139, 0xc038aa3b, v139
	v_exp_f32_e32 v138, v138
	v_exp_f32_e32 v139, v139
	v_add_f32_e32 v138, 1.0, v138
	v_add_f32_e32 v139, 1.0, v139
	v_rcp_f32_e32 v138, v138
	v_rcp_f32_e32 v139, v139
	s_nop 0
	v_pk_mul_f32 v[120:121], v[120:121], v[138:139]
	v_mul_f32_e32 v138, 0x3d372713, v122
	v_mul_f32_e32 v139, 0x3d372713, v123
	v_mul_f32_e32 v138, v122, v138
	v_mul_f32_e32 v139, v123, v139
	v_fma_f32 v138, v122, v138, v122
	v_fma_f32 v139, v123, v139, v123
	v_mul_f32_e32 v138, 0x3f4c422a, v138
	v_mul_f32_e32 v139, 0x3f4c422a, v139
	v_mul_f32_e32 v138, 0xc038aa3b, v138
	v_mul_f32_e32 v139, 0xc038aa3b, v139
	v_exp_f32_e32 v138, v138
	v_exp_f32_e32 v139, v139
	v_cvt_pk_bf16_f32 v120, v120, v121
	v_add_f32_e32 v138, 1.0, v138
	v_add_f32_e32 v139, 1.0, v139
	v_rcp_f32_e32 v138, v138
	v_rcp_f32_e32 v139, v139
	s_nop 0
	v_pk_mul_f32 v[122:123], v[122:123], v[138:139]
	s_nop 0
	v_cvt_pk_bf16_f32 v121, v122, v123
	ds_write2_b64 v126, v[136:137], v[120:121] offset1:4
	v_mul_f32_e32 v120, 0x3d372713, v116
	v_mul_f32_e32 v121, 0x3d372713, v117
	v_mul_f32_e32 v120, v116, v120
	v_mul_f32_e32 v121, v117, v121
	v_fma_f32 v120, v116, v120, v116
	v_fma_f32 v121, v117, v121, v117
	v_mul_f32_e32 v120, 0x3f4c422a, v120
	v_mul_f32_e32 v121, 0x3f4c422a, v121
	v_mul_f32_e32 v120, 0xc038aa3b, v120
	v_mul_f32_e32 v121, 0xc038aa3b, v121
	v_exp_f32_e32 v120, v120
	v_exp_f32_e32 v121, v121
	v_add_f32_e32 v120, 1.0, v120
	v_add_f32_e32 v121, 1.0, v121
	v_rcp_f32_e32 v120, v120
	v_rcp_f32_e32 v121, v121
	s_nop 0
	v_pk_mul_f32 v[116:117], v[116:117], v[120:121]
	v_mul_f32_e32 v120, 0x3d372713, v118
	v_mul_f32_e32 v121, 0x3d372713, v119
	v_mul_f32_e32 v120, v118, v120
	v_mul_f32_e32 v121, v119, v121
	v_fma_f32 v120, v118, v120, v118
	v_fma_f32 v121, v119, v121, v119
	v_mul_f32_e32 v120, 0x3f4c422a, v120
	v_mul_f32_e32 v121, 0x3f4c422a, v121
	v_mul_f32_e32 v120, 0xc038aa3b, v120
	v_mul_f32_e32 v121, 0xc038aa3b, v121
	v_exp_f32_e32 v120, v120
	v_exp_f32_e32 v121, v121
	v_cvt_pk_bf16_f32 v116, v116, v117
	v_add_f32_e32 v120, 1.0, v120
	v_add_f32_e32 v121, 1.0, v121
	v_rcp_f32_e32 v120, v120
	v_rcp_f32_e32 v121, v121
	s_nop 0
	v_pk_mul_f32 v[118:119], v[118:119], v[120:121]
	s_nop 0
	v_cvt_pk_bf16_f32 v117, v118, v119
	v_mul_f32_e32 v118, 0x3d372713, v112
	v_mul_f32_e32 v119, 0x3d372713, v113
	v_mul_f32_e32 v118, v112, v118
	v_mul_f32_e32 v119, v113, v119
	v_fma_f32 v118, v112, v118, v112
	v_fma_f32 v119, v113, v119, v113
	v_mul_f32_e32 v118, 0x3f4c422a, v118
	v_mul_f32_e32 v119, 0x3f4c422a, v119
	v_mul_f32_e32 v118, 0xc038aa3b, v118
	v_mul_f32_e32 v119, 0xc038aa3b, v119
	v_exp_f32_e32 v118, v118
	v_exp_f32_e32 v119, v119
	v_add_f32_e32 v118, 1.0, v118
	v_add_f32_e32 v119, 1.0, v119
	v_rcp_f32_e32 v118, v118
	v_rcp_f32_e32 v119, v119
	s_nop 0
	v_pk_mul_f32 v[112:113], v[112:113], v[118:119]
	v_mul_f32_e32 v118, 0x3d372713, v114
	v_mul_f32_e32 v119, 0x3d372713, v115
	v_mul_f32_e32 v118, v114, v118
	v_mul_f32_e32 v119, v115, v119
	v_fma_f32 v118, v114, v118, v114
	v_fma_f32 v119, v115, v119, v115
	v_mul_f32_e32 v118, 0x3f4c422a, v118
	v_mul_f32_e32 v119, 0x3f4c422a, v119
	v_mul_f32_e32 v118, 0xc038aa3b, v118
	v_mul_f32_e32 v119, 0xc038aa3b, v119
	v_exp_f32_e32 v118, v118
	v_exp_f32_e32 v119, v119
	v_cvt_pk_bf16_f32 v112, v112, v113
	v_add_f32_e32 v118, 1.0, v118
	v_add_f32_e32 v119, 1.0, v119
	v_rcp_f32_e32 v118, v118
	v_rcp_f32_e32 v119, v119
	s_nop 0
	v_pk_mul_f32 v[114:115], v[114:115], v[118:119]
	s_nop 0
	v_cvt_pk_bf16_f32 v113, v114, v115
	ds_write2_b64 v126, v[116:117], v[112:113] offset0:8 offset1:12
	v_mov_b32_e32 v112, v245
	v_pk_mul_f32 v[108:109], v[108:109], v[112:113] op_sel_hi:[1,0]
	s_nop 0
	v_mul_f32_e32 v113, 0x3d372713, v108
	v_mul_f32_e32 v113, v108, v113
	v_fma_f32 v113, v108, v113, v108
	v_mul_f32_e32 v113, 0x3f4c422a, v113
	v_mul_f32_e32 v113, 0xc038aa3b, v113
	v_exp_f32_e32 v113, v113
	s_nop 0
	v_add_f32_e32 v113, 1.0, v113
	v_rcp_f32_e32 v114, v113
	v_mul_f32_e32 v113, 0x3d372713, v109
	v_mul_f32_e32 v113, v109, v113
	v_fma_f32 v113, v109, v113, v109
	v_mul_f32_e32 v113, 0x3f4c422a, v113
	v_mul_f32_e32 v113, 0xc038aa3b, v113
	v_exp_f32_e32 v113, v113
	s_nop 0
	v_add_f32_e32 v113, 1.0, v113
	v_pk_mul_f32 v[110:111], v[110:111], v[112:113] op_sel_hi:[1,0]
	v_rcp_f32_e32 v115, v113
	v_mul_f32_e32 v113, 0x3d372713, v110
	v_mul_f32_e32 v113, v110, v113
	v_fma_f32 v113, v110, v113, v110
	v_mul_f32_e32 v113, 0x3f4c422a, v113
	v_mul_f32_e32 v113, 0xc038aa3b, v113
	v_exp_f32_e32 v113, v113
	v_pk_mul_f32 v[108:109], v[108:109], v[114:115]
	v_add_f32_e32 v113, 1.0, v113
	v_rcp_f32_e32 v114, v113
	v_mul_f32_e32 v113, 0x3d372713, v111
	v_mul_f32_e32 v113, v111, v113
	v_fma_f32 v113, v111, v113, v111
	v_mul_f32_e32 v113, 0x3f4c422a, v113
	v_mul_f32_e32 v113, 0xc038aa3b, v113
	v_exp_f32_e32 v113, v113
	v_cvt_pk_bf16_f32 v108, v108, v109
	v_add_f32_e32 v113, 1.0, v113
	v_rcp_f32_e32 v115, v113
	v_pk_mul_f32 v[104:105], v[104:105], v[112:113] op_sel_hi:[1,0]
	v_pk_mul_f32 v[106:107], v[106:107], v[112:113] op_sel_hi:[1,0]
	v_pk_mul_f32 v[100:101], v[100:101], v[112:113] op_sel_hi:[1,0]
	v_pk_mul_f32 v[110:111], v[110:111], v[114:115]
	v_pk_mul_f32 v[102:103], v[102:103], v[112:113] op_sel_hi:[1,0]
	v_cvt_pk_bf16_f32 v109, v110, v111
; DI unsigned pk2(float a, float b) { f32x2 v = {a, b}; bf16x2_t r = __builtin_convertvector(v, bf16x2_t); return __builtin_bit_cast(unsigned, r); }
;     DI void operator()(gacc_t& acc, int pm, int pn, char* lds, int tid, int wr, int wc, int lane) const {
;     ...
;         for (int m = 0; m < 8; ++m) {
;             const float r = rl[m * 16];
; #pragma unroll
;             for (int n = 0; n < 4; ++n) {
;                 float g[4];
; #pragma unroll
;                 for (int j = 0; j < 4; ++j) {
;                     const float x = acc[m][n][j] * r;
;                     const float u = 0.7978845608028654f * (x + 0.044715f * x * x * x);
;                     const float e = __builtin_amdgcn_exp2f(-2.885390081777927f * u);
;                     g[j] = x * __builtin_amdgcn_rcpf(1.0f + e);
;                 }
;                 u32x2 w; w.x = pk2(g[0], g[1]); w.y = pk2(g[2], g[3]);
;                 *(u32x2*)(lbase + m * 16 * 528 + n * 32) = w;
;             }
;             __builtin_amdgcn_sched_barrier(0);
	v_mul_f32_e32 v110, 0x3d372713, v104
	v_mul_f32_e32 v111, 0x3d372713, v105
	v_mul_f32_e32 v110, v104, v110
	v_mul_f32_e32 v111, v105, v111
	v_fma_f32 v110, v104, v110, v104
	v_fma_f32 v111, v105, v111, v105
	v_mul_f32_e32 v110, 0x3f4c422a, v110
	v_mul_f32_e32 v111, 0x3f4c422a, v111
	v_mul_f32_e32 v110, 0xc038aa3b, v110
	v_mul_f32_e32 v111, 0xc038aa3b, v111
	v_exp_f32_e32 v110, v110
	v_exp_f32_e32 v111, v111
	v_pk_mul_f32 v[96:97], v[96:97], v[112:113] op_sel_hi:[1,0]
	v_pk_mul_f32 v[98:99], v[98:99], v[112:113] op_sel_hi:[1,0]
	v_add_f32_e32 v110, 1.0, v110
	v_add_f32_e32 v111, 1.0, v111
	v_rcp_f32_e32 v110, v110
	v_rcp_f32_e32 v111, v111
	s_nop 0
	v_pk_mul_f32 v[104:105], v[104:105], v[110:111]
	v_mul_f32_e32 v110, 0x3d372713, v106
	v_mul_f32_e32 v111, 0x3d372713, v107
	v_mul_f32_e32 v110, v106, v110
	v_mul_f32_e32 v111, v107, v111
	v_fma_f32 v110, v106, v110, v106
	v_fma_f32 v111, v107, v111, v107
	v_mul_f32_e32 v110, 0x3f4c422a, v110
	v_mul_f32_e32 v111, 0x3f4c422a, v111
	v_mul_f32_e32 v110, 0xc038aa3b, v110
	v_mul_f32_e32 v111, 0xc038aa3b, v111
	v_exp_f32_e32 v110, v110
	v_exp_f32_e32 v111, v111
	v_cvt_pk_bf16_f32 v104, v104, v105
	v_add_f32_e32 v110, 1.0, v110
	v_add_f32_e32 v111, 1.0, v111
	v_rcp_f32_e32 v110, v110
	v_rcp_f32_e32 v111, v111
	s_nop 0
	v_pk_mul_f32 v[106:107], v[106:107], v[110:111]
	s_nop 0
	v_cvt_pk_bf16_f32 v105, v106, v107
	v_add_u32_e32 v106, 0x2000, v126
	ds_write2_b64 v106, v[108:109], v[104:105] offset0:32 offset1:36
	v_mul_f32_e32 v104, 0x3d372713, v100
	v_mul_f32_e32 v105, 0x3d372713, v101
	v_mul_f32_e32 v104, v100, v104
	v_mul_f32_e32 v105, v101, v105
	v_fma_f32 v104, v100, v104, v100
	v_fma_f32 v105, v101, v105, v101
	v_mul_f32_e32 v104, 0x3f4c422a, v104
	v_mul_f32_e32 v105, 0x3f4c422a, v105
	v_mul_f32_e32 v104, 0xc038aa3b, v104
	v_mul_f32_e32 v105, 0xc038aa3b, v105
	v_exp_f32_e32 v104, v104
	v_exp_f32_e32 v105, v105
	v_add_f32_e32 v104, 1.0, v104
	v_add_f32_e32 v105, 1.0, v105
	v_rcp_f32_e32 v104, v104
	v_rcp_f32_e32 v105, v105
	s_nop 0
	v_pk_mul_f32 v[100:101], v[100:101], v[104:105]
	v_mul_f32_e32 v104, 0x3d372713, v102
	v_mul_f32_e32 v105, 0x3d372713, v103
	v_mul_f32_e32 v104, v102, v104
	v_mul_f32_e32 v105, v103, v105
	v_fma_f32 v104, v102, v104, v102
	v_fma_f32 v105, v103, v105, v103
	v_mul_f32_e32 v104, 0x3f4c422a, v104
	v_mul_f32_e32 v105, 0x3f4c422a, v105
	v_mul_f32_e32 v104, 0xc038aa3b, v104
	v_mul_f32_e32 v105, 0xc038aa3b, v105
	v_exp_f32_e32 v104, v104
	v_exp_f32_e32 v105, v105
	v_cvt_pk_bf16_f32 v100, v100, v101
	v_add_f32_e32 v104, 1.0, v104
	v_add_f32_e32 v105, 1.0, v105
	v_rcp_f32_e32 v104, v104
	v_rcp_f32_e32 v105, v105
	s_nop 0
	v_pk_mul_f32 v[102:103], v[102:103], v[104:105]
	s_nop 0
	v_cvt_pk_bf16_f32 v101, v102, v103
	v_mul_f32_e32 v102, 0x3d372713, v96
	v_mul_f32_e32 v103, 0x3d372713, v97
	v_mul_f32_e32 v102, v96, v102
	v_mul_f32_e32 v103, v97, v103
	v_fma_f32 v102, v96, v102, v96
	v_fma_f32 v103, v97, v103, v97
	v_mul_f32_e32 v102, 0x3f4c422a, v102
	v_mul_f32_e32 v103, 0x3f4c422a, v103
	v_mul_f32_e32 v102, 0xc038aa3b, v102
	v_mul_f32_e32 v103, 0xc038aa3b, v103
	v_exp_f32_e32 v102, v102
	v_exp_f32_e32 v103, v103
	v_add_f32_e32 v102, 1.0, v102
	v_add_f32_e32 v103, 1.0, v103
	v_rcp_f32_e32 v102, v102
	v_rcp_f32_e32 v103, v103
	s_nop 0
	v_pk_mul_f32 v[96:97], v[96:97], v[102:103]
	v_mul_f32_e32 v102, 0x3d372713, v98
	v_mul_f32_e32 v103, 0x3d372713, v99
	v_mul_f32_e32 v102, v98, v102
	v_mul_f32_e32 v103, v99, v103
	v_fma_f32 v102, v98, v102, v98
	v_fma_f32 v103, v99, v103, v99
	v_mul_f32_e32 v102, 0x3f4c422a, v102
	v_mul_f32_e32 v103, 0x3f4c422a, v103
	v_mul_f32_e32 v102, 0xc038aa3b, v102
	v_mul_f32_e32 v103, 0xc038aa3b, v103
	v_exp_f32_e32 v102, v102
	v_exp_f32_e32 v103, v103
	v_cvt_pk_bf16_f32 v96, v96, v97
	v_add_f32_e32 v102, 1.0, v102
	v_add_f32_e32 v103, 1.0, v103
	v_rcp_f32_e32 v102, v102
	v_rcp_f32_e32 v103, v103
	s_nop 0
	v_pk_mul_f32 v[98:99], v[98:99], v[102:103]
	s_nop 0
	v_cvt_pk_bf16_f32 v97, v98, v99
	ds_write2_b64 v106, v[100:101], v[96:97] offset0:40 offset1:44
	v_mov_b32_e32 v96, v246
	v_pk_mul_f32 v[92:93], v[92:93], v[96:97] op_sel_hi:[1,0]
	s_nop 0
	v_mul_f32_e32 v97, 0x3d372713, v92
	v_mul_f32_e32 v97, v92, v97
	v_fma_f32 v97, v92, v97, v92
	v_mul_f32_e32 v97, 0x3f4c422a, v97
	v_mul_f32_e32 v97, 0xc038aa3b, v97
	v_exp_f32_e32 v97, v97
	s_nop 0
	v_add_f32_e32 v97, 1.0, v97
	v_rcp_f32_e32 v98, v97
	v_mul_f32_e32 v97, 0x3d372713, v93
	v_mul_f32_e32 v97, v93, v97
	v_fma_f32 v97, v93, v97, v93
	v_mul_f32_e32 v97, 0x3f4c422a, v97
	v_mul_f32_e32 v97, 0xc038aa3b, v97
	v_exp_f32_e32 v97, v97
	s_nop 0
	v_add_f32_e32 v97, 1.0, v97
	v_pk_mul_f32 v[94:95], v[94:95], v[96:97] op_sel_hi:[1,0]
	v_rcp_f32_e32 v99, v97
	v_mul_f32_e32 v97, 0x3d372713, v94
	v_mul_f32_e32 v97, v94, v97
	v_fma_f32 v97, v94, v97, v94
	v_mul_f32_e32 v97, 0x3f4c422a, v97
	v_mul_f32_e32 v97, 0xc038aa3b, v97
	v_exp_f32_e32 v97, v97
	v_pk_mul_f32 v[92:93], v[92:93], v[98:99]
	v_add_f32_e32 v97, 1.0, v97
	v_rcp_f32_e32 v98, v97
	v_mul_f32_e32 v97, 0x3d372713, v95
	v_mul_f32_e32 v97, v95, v97
	v_fma_f32 v97, v95, v97, v95
	v_mul_f32_e32 v97, 0x3f4c422a, v97
	v_mul_f32_e32 v97, 0xc038aa3b, v97
	v_exp_f32_e32 v97, v97
	v_cvt_pk_bf16_f32 v92, v92, v93
	v_add_f32_e32 v97, 1.0, v97
	v_rcp_f32_e32 v99, v97
	v_pk_mul_f32 v[88:89], v[88:89], v[96:97] op_sel_hi:[1,0]
	v_pk_mul_f32 v[90:91], v[90:91], v[96:97] op_sel_hi:[1,0]
	v_pk_mul_f32 v[84:85], v[84:85], v[96:97] op_sel_hi:[1,0]
	v_pk_mul_f32 v[94:95], v[94:95], v[98:99]
	v_pk_mul_f32 v[86:87], v[86:87], v[96:97] op_sel_hi:[1,0]
	v_cvt_pk_bf16_f32 v93, v94, v95
	v_mul_f32_e32 v94, 0x3d372713, v88
	v_mul_f32_e32 v95, 0x3d372713, v89
	v_mul_f32_e32 v94, v88, v94
; DI unsigned pk2(float a, float b) { f32x2 v = {a, b}; bf16x2_t r = __builtin_convertvector(v, bf16x2_t); return __builtin_bit_cast(unsigned, r); }
;     DI void operator()(gacc_t& acc, int pm, int pn, char* lds, int tid, int wr, int wc, int lane) const {
;     ...
;         for (int m = 0; m < 8; ++m) {
;             const float r = rl[m * 16];
; #pragma unroll
;             for (int n = 0; n < 4; ++n) {
;                 float g[4];
; #pragma unroll
;                 for (int j = 0; j < 4; ++j) {
;                     const float x = acc[m][n][j] * r;
;                     const float u = 0.7978845608028654f * (x + 0.044715f * x * x * x);
;                     const float e = __builtin_amdgcn_exp2f(-2.885390081777927f * u);
;                     g[j] = x * __builtin_amdgcn_rcpf(1.0f + e);
;                 }
;                 u32x2 w; w.x = pk2(g[0], g[1]); w.y = pk2(g[2], g[3]);
;                 *(u32x2*)(lbase + m * 16 * 528 + n * 32) = w;
;             }
;             __builtin_amdgcn_sched_barrier(0);
	v_mul_f32_e32 v95, v89, v95
	v_fma_f32 v94, v88, v94, v88
	v_fma_f32 v95, v89, v95, v89
	v_mul_f32_e32 v94, 0x3f4c422a, v94
	v_mul_f32_e32 v95, 0x3f4c422a, v95
	v_mul_f32_e32 v94, 0xc038aa3b, v94
	v_mul_f32_e32 v95, 0xc038aa3b, v95
	v_exp_f32_e32 v94, v94
	v_exp_f32_e32 v95, v95
	v_pk_mul_f32 v[80:81], v[80:81], v[96:97] op_sel_hi:[1,0]
	v_pk_mul_f32 v[82:83], v[82:83], v[96:97] op_sel_hi:[1,0]
	v_add_f32_e32 v94, 1.0, v94
	v_add_f32_e32 v95, 1.0, v95
	v_rcp_f32_e32 v94, v94
	v_rcp_f32_e32 v95, v95
	s_nop 0
	v_pk_mul_f32 v[88:89], v[88:89], v[94:95]
	v_mul_f32_e32 v94, 0x3d372713, v90
	v_mul_f32_e32 v95, 0x3d372713, v91
	v_mul_f32_e32 v94, v90, v94
	v_mul_f32_e32 v95, v91, v95
	v_fma_f32 v94, v90, v94, v90
	v_fma_f32 v95, v91, v95, v91
	v_mul_f32_e32 v94, 0x3f4c422a, v94
	v_mul_f32_e32 v95, 0x3f4c422a, v95
	v_mul_f32_e32 v94, 0xc038aa3b, v94
	v_mul_f32_e32 v95, 0xc038aa3b, v95
	v_exp_f32_e32 v94, v94
	v_exp_f32_e32 v95, v95
	v_cvt_pk_bf16_f32 v88, v88, v89
	v_add_f32_e32 v94, 1.0, v94
	v_add_f32_e32 v95, 1.0, v95
	v_rcp_f32_e32 v94, v94
	v_rcp_f32_e32 v95, v95
	s_nop 0
	v_pk_mul_f32 v[90:91], v[90:91], v[94:95]
	s_nop 0
	v_cvt_pk_bf16_f32 v89, v90, v91
	v_add_u32_e32 v90, 0x4000, v126
	ds_write2_b64 v90, v[92:93], v[88:89] offset0:64 offset1:68
	v_mul_f32_e32 v88, 0x3d372713, v84
	v_mul_f32_e32 v89, 0x3d372713, v85
	v_mul_f32_e32 v88, v84, v88
	v_mul_f32_e32 v89, v85, v89
	v_fma_f32 v88, v84, v88, v84
	v_fma_f32 v89, v85, v89, v85
	v_mul_f32_e32 v88, 0x3f4c422a, v88
	v_mul_f32_e32 v89, 0x3f4c422a, v89
	v_mul_f32_e32 v88, 0xc038aa3b, v88
	v_mul_f32_e32 v89, 0xc038aa3b, v89
	v_exp_f32_e32 v88, v88
	v_exp_f32_e32 v89, v89
	v_add_f32_e32 v88, 1.0, v88
	v_add_f32_e32 v89, 1.0, v89
	v_rcp_f32_e32 v88, v88
	v_rcp_f32_e32 v89, v89
	s_nop 0
	v_pk_mul_f32 v[84:85], v[84:85], v[88:89]
	v_mul_f32_e32 v88, 0x3d372713, v86
	v_mul_f32_e32 v89, 0x3d372713, v87
	v_mul_f32_e32 v88, v86, v88
	v_mul_f32_e32 v89, v87, v89
	v_fma_f32 v88, v86, v88, v86
	v_fma_f32 v89, v87, v89, v87
	v_mul_f32_e32 v88, 0x3f4c422a, v88
	v_mul_f32_e32 v89, 0x3f4c422a, v89
	v_mul_f32_e32 v88, 0xc038aa3b, v88
	v_mul_f32_e32 v89, 0xc038aa3b, v89
	v_exp_f32_e32 v88, v88
	v_exp_f32_e32 v89, v89
	v_cvt_pk_bf16_f32 v84, v84, v85
	v_add_f32_e32 v88, 1.0, v88
	v_add_f32_e32 v89, 1.0, v89
	v_rcp_f32_e32 v88, v88
	v_rcp_f32_e32 v89, v89
	s_nop 0
	v_pk_mul_f32 v[86:87], v[86:87], v[88:89]
	s_nop 0
	v_cvt_pk_bf16_f32 v85, v86, v87
	v_mul_f32_e32 v86, 0x3d372713, v80
	v_mul_f32_e32 v87, 0x3d372713, v81
	v_mul_f32_e32 v86, v80, v86
	v_mul_f32_e32 v87, v81, v87
	v_fma_f32 v86, v80, v86, v80
	v_fma_f32 v87, v81, v87, v81
	v_mul_f32_e32 v86, 0x3f4c422a, v86
	v_mul_f32_e32 v87, 0x3f4c422a, v87
	v_mul_f32_e32 v86, 0xc038aa3b, v86
	v_mul_f32_e32 v87, 0xc038aa3b, v87
	v_exp_f32_e32 v86, v86
	v_exp_f32_e32 v87, v87
	v_add_f32_e32 v86, 1.0, v86
	v_add_f32_e32 v87, 1.0, v87
	v_rcp_f32_e32 v86, v86
	v_rcp_f32_e32 v87, v87
	s_nop 0
	v_pk_mul_f32 v[80:81], v[80:81], v[86:87]
	v_mul_f32_e32 v86, 0x3d372713, v82
	v_mul_f32_e32 v87, 0x3d372713, v83
	v_mul_f32_e32 v86, v82, v86
	v_mul_f32_e32 v87, v83, v87
	v_fma_f32 v86, v82, v86, v82
	v_fma_f32 v87, v83, v87, v83
	v_mul_f32_e32 v86, 0x3f4c422a, v86
	v_mul_f32_e32 v87, 0x3f4c422a, v87
	v_mul_f32_e32 v86, 0xc038aa3b, v86
	v_mul_f32_e32 v87, 0xc038aa3b, v87
	v_exp_f32_e32 v86, v86
	v_exp_f32_e32 v87, v87
	v_cvt_pk_bf16_f32 v80, v80, v81
	v_add_f32_e32 v86, 1.0, v86
	v_add_f32_e32 v87, 1.0, v87
	v_rcp_f32_e32 v86, v86
	v_rcp_f32_e32 v87, v87
	s_nop 0
	v_pk_mul_f32 v[82:83], v[82:83], v[86:87]
	s_nop 0
	v_cvt_pk_bf16_f32 v81, v82, v83
	ds_write2_b64 v90, v[84:85], v[80:81] offset0:72 offset1:76
	v_mov_b32_e32 v80, v247
	v_pk_mul_f32 v[76:77], v[76:77], v[80:81] op_sel_hi:[1,0]
	s_nop 0
	v_mul_f32_e32 v81, 0x3d372713, v76
	v_mul_f32_e32 v81, v76, v81
	v_fma_f32 v81, v76, v81, v76
	v_mul_f32_e32 v81, 0x3f4c422a, v81
	v_mul_f32_e32 v81, 0xc038aa3b, v81
	v_exp_f32_e32 v81, v81
	s_nop 0
	v_add_f32_e32 v81, 1.0, v81
	v_rcp_f32_e32 v82, v81
	v_mul_f32_e32 v81, 0x3d372713, v77
	v_mul_f32_e32 v81, v77, v81
	v_fma_f32 v81, v77, v81, v77
	v_mul_f32_e32 v81, 0x3f4c422a, v81
	v_mul_f32_e32 v81, 0xc038aa3b, v81
	v_exp_f32_e32 v81, v81
	s_nop 0
	v_add_f32_e32 v81, 1.0, v81
	v_pk_mul_f32 v[78:79], v[78:79], v[80:81] op_sel_hi:[1,0]
	v_rcp_f32_e32 v83, v81
	v_mul_f32_e32 v81, 0x3d372713, v78
	v_mul_f32_e32 v81, v78, v81
	v_fma_f32 v81, v78, v81, v78
	v_mul_f32_e32 v81, 0x3f4c422a, v81
	v_mul_f32_e32 v81, 0xc038aa3b, v81
	v_exp_f32_e32 v81, v81
	v_pk_mul_f32 v[76:77], v[76:77], v[82:83]
	v_add_f32_e32 v81, 1.0, v81
	v_rcp_f32_e32 v82, v81
	v_mul_f32_e32 v81, 0x3d372713, v79
	v_mul_f32_e32 v81, v79, v81
	v_fma_f32 v81, v79, v81, v79
	v_mul_f32_e32 v81, 0x3f4c422a, v81
	v_mul_f32_e32 v81, 0xc038aa3b, v81
	v_exp_f32_e32 v81, v81
	v_cvt_pk_bf16_f32 v76, v76, v77
	v_add_f32_e32 v81, 1.0, v81
	v_rcp_f32_e32 v83, v81
	v_pk_mul_f32 v[72:73], v[72:73], v[80:81] op_sel_hi:[1,0]
	v_pk_mul_f32 v[74:75], v[74:75], v[80:81] op_sel_hi:[1,0]
	v_pk_mul_f32 v[68:69], v[68:69], v[80:81] op_sel_hi:[1,0]
	v_pk_mul_f32 v[78:79], v[78:79], v[82:83]
	v_pk_mul_f32 v[70:71], v[70:71], v[80:81] op_sel_hi:[1,0]
	v_cvt_pk_bf16_f32 v77, v78, v79
	v_mul_f32_e32 v78, 0x3d372713, v72
	v_mul_f32_e32 v79, 0x3d372713, v73
	v_mul_f32_e32 v78, v72, v78
	v_mul_f32_e32 v79, v73, v79
	v_fma_f32 v78, v72, v78, v72
	v_fma_f32 v79, v73, v79, v73
	v_mul_f32_e32 v78, 0x3f4c422a, v78
	v_mul_f32_e32 v79, 0x3f4c422a, v79
	v_mul_f32_e32 v78, 0xc038aa3b, v78
	v_mul_f32_e32 v79, 0xc038aa3b, v79
	v_exp_f32_e32 v78, v78
	v_exp_f32_e32 v79, v79
	v_pk_mul_f32 v[64:65], v[64:65], v[80:81] op_sel_hi:[1,0]
; DI unsigned pk2(float a, float b) { f32x2 v = {a, b}; bf16x2_t r = __builtin_convertvector(v, bf16x2_t); return __builtin_bit_cast(unsigned, r); }
;     DI void operator()(gacc_t& acc, int pm, int pn, char* lds, int tid, int wr, int wc, int lane) const {
;     ...
;         for (int m = 0; m < 8; ++m) {
;             const float r = rl[m * 16];
; #pragma unroll
;             for (int n = 0; n < 4; ++n) {
;                 float g[4];
; #pragma unroll
;                 for (int j = 0; j < 4; ++j) {
;                     const float x = acc[m][n][j] * r;
;                     const float u = 0.7978845608028654f * (x + 0.044715f * x * x * x);
;                     const float e = __builtin_amdgcn_exp2f(-2.885390081777927f * u);
;                     g[j] = x * __builtin_amdgcn_rcpf(1.0f + e);
;                 }
;                 u32x2 w; w.x = pk2(g[0], g[1]); w.y = pk2(g[2], g[3]);
;                 *(u32x2*)(lbase + m * 16 * 528 + n * 32) = w;
;             }
;             __builtin_amdgcn_sched_barrier(0);
	v_pk_mul_f32 v[66:67], v[66:67], v[80:81] op_sel_hi:[1,0]
	v_add_f32_e32 v78, 1.0, v78
	v_add_f32_e32 v79, 1.0, v79
	v_rcp_f32_e32 v78, v78
	v_rcp_f32_e32 v79, v79
	s_nop 0
	v_pk_mul_f32 v[72:73], v[72:73], v[78:79]
	v_mul_f32_e32 v78, 0x3d372713, v74
	v_mul_f32_e32 v79, 0x3d372713, v75
	v_mul_f32_e32 v78, v74, v78
	v_mul_f32_e32 v79, v75, v79
	v_fma_f32 v78, v74, v78, v74
	v_fma_f32 v79, v75, v79, v75
	v_mul_f32_e32 v78, 0x3f4c422a, v78
	v_mul_f32_e32 v79, 0x3f4c422a, v79
	v_mul_f32_e32 v78, 0xc038aa3b, v78
	v_mul_f32_e32 v79, 0xc038aa3b, v79
	v_exp_f32_e32 v78, v78
	v_exp_f32_e32 v79, v79
	v_cvt_pk_bf16_f32 v72, v72, v73
	v_add_f32_e32 v78, 1.0, v78
	v_add_f32_e32 v79, 1.0, v79
	v_rcp_f32_e32 v78, v78
	v_rcp_f32_e32 v79, v79
	s_nop 0
	v_pk_mul_f32 v[74:75], v[74:75], v[78:79]
	s_nop 0
	v_cvt_pk_bf16_f32 v73, v74, v75
	v_add_u32_e32 v74, 0x6000, v126
	ds_write2_b64 v74, v[76:77], v[72:73] offset0:96 offset1:100
	v_mul_f32_e32 v72, 0x3d372713, v68
	v_mul_f32_e32 v73, 0x3d372713, v69
	v_mul_f32_e32 v72, v68, v72
	v_mul_f32_e32 v73, v69, v73
	v_fma_f32 v72, v68, v72, v68
	v_fma_f32 v73, v69, v73, v69
	v_mul_f32_e32 v72, 0x3f4c422a, v72
	v_mul_f32_e32 v73, 0x3f4c422a, v73
	v_mul_f32_e32 v72, 0xc038aa3b, v72
	v_mul_f32_e32 v73, 0xc038aa3b, v73
	v_exp_f32_e32 v72, v72
	v_exp_f32_e32 v73, v73
	v_add_f32_e32 v72, 1.0, v72
	v_add_f32_e32 v73, 1.0, v73
	v_rcp_f32_e32 v72, v72
	v_rcp_f32_e32 v73, v73
	s_nop 0
	v_pk_mul_f32 v[68:69], v[68:69], v[72:73]
	v_mul_f32_e32 v72, 0x3d372713, v70
	v_mul_f32_e32 v73, 0x3d372713, v71
	v_mul_f32_e32 v72, v70, v72
	v_mul_f32_e32 v73, v71, v73
	v_fma_f32 v72, v70, v72, v70
	v_fma_f32 v73, v71, v73, v71
	v_mul_f32_e32 v72, 0x3f4c422a, v72
	v_mul_f32_e32 v73, 0x3f4c422a, v73
	v_mul_f32_e32 v72, 0xc038aa3b, v72
	v_mul_f32_e32 v73, 0xc038aa3b, v73
	v_exp_f32_e32 v72, v72
	v_exp_f32_e32 v73, v73
	v_cvt_pk_bf16_f32 v68, v68, v69
	v_add_f32_e32 v72, 1.0, v72
	v_add_f32_e32 v73, 1.0, v73
	v_rcp_f32_e32 v72, v72
	v_rcp_f32_e32 v73, v73
	s_nop 0
	v_pk_mul_f32 v[70:71], v[70:71], v[72:73]
	s_nop 0
	v_cvt_pk_bf16_f32 v69, v70, v71
	v_mul_f32_e32 v70, 0x3d372713, v64
	v_mul_f32_e32 v71, 0x3d372713, v65
	v_mul_f32_e32 v70, v64, v70
	v_mul_f32_e32 v71, v65, v71
	v_fma_f32 v70, v64, v70, v64
	v_fma_f32 v71, v65, v71, v65
	v_mul_f32_e32 v70, 0x3f4c422a, v70
	v_mul_f32_e32 v71, 0x3f4c422a, v71
	v_mul_f32_e32 v70, 0xc038aa3b, v70
	v_mul_f32_e32 v71, 0xc038aa3b, v71
	v_exp_f32_e32 v70, v70
	v_exp_f32_e32 v71, v71
	v_add_f32_e32 v70, 1.0, v70
	v_add_f32_e32 v71, 1.0, v71
	v_rcp_f32_e32 v70, v70
	v_rcp_f32_e32 v71, v71
	s_nop 0
	v_pk_mul_f32 v[64:65], v[64:65], v[70:71]
	v_mul_f32_e32 v70, 0x3d372713, v66
	v_mul_f32_e32 v71, 0x3d372713, v67
	v_mul_f32_e32 v70, v66, v70
	v_mul_f32_e32 v71, v67, v71
	v_fma_f32 v70, v66, v70, v66
	v_fma_f32 v71, v67, v71, v67
	v_mul_f32_e32 v70, 0x3f4c422a, v70
	v_mul_f32_e32 v71, 0x3f4c422a, v71
	v_mul_f32_e32 v70, 0xc038aa3b, v70
	v_mul_f32_e32 v71, 0xc038aa3b, v71
	v_exp_f32_e32 v70, v70
	v_exp_f32_e32 v71, v71
	v_cvt_pk_bf16_f32 v64, v64, v65
	v_add_f32_e32 v70, 1.0, v70
	v_add_f32_e32 v71, 1.0, v71
	v_rcp_f32_e32 v70, v70
	v_rcp_f32_e32 v71, v71
	s_nop 0
	v_pk_mul_f32 v[66:67], v[66:67], v[70:71]
	s_nop 0
	v_cvt_pk_bf16_f32 v65, v66, v67
	ds_write2_b64 v74, v[68:69], v[64:65] offset0:104 offset1:108
	v_mov_b32_e32 v64, v248
	v_pk_mul_f32 v[60:61], v[60:61], v[64:65] op_sel_hi:[1,0]
	s_nop 0
	v_mul_f32_e32 v65, 0x3d372713, v60
	v_mul_f32_e32 v65, v60, v65
	v_fma_f32 v65, v60, v65, v60
	v_mul_f32_e32 v65, 0x3f4c422a, v65
	v_mul_f32_e32 v65, 0xc038aa3b, v65
	v_exp_f32_e32 v65, v65
	s_nop 0
	v_add_f32_e32 v65, 1.0, v65
	v_rcp_f32_e32 v66, v65
	v_mul_f32_e32 v65, 0x3d372713, v61
	v_mul_f32_e32 v65, v61, v65
	v_fma_f32 v65, v61, v65, v61
	v_mul_f32_e32 v65, 0x3f4c422a, v65
	v_mul_f32_e32 v65, 0xc038aa3b, v65
	v_exp_f32_e32 v65, v65
	s_nop 0
	v_add_f32_e32 v65, 1.0, v65
	v_pk_mul_f32 v[62:63], v[62:63], v[64:65] op_sel_hi:[1,0]
	v_rcp_f32_e32 v67, v65
	v_mul_f32_e32 v65, 0x3d372713, v62
	v_mul_f32_e32 v65, v62, v65
	v_fma_f32 v65, v62, v65, v62
	v_mul_f32_e32 v65, 0x3f4c422a, v65
	v_mul_f32_e32 v65, 0xc038aa3b, v65
	v_exp_f32_e32 v65, v65
	v_pk_mul_f32 v[60:61], v[60:61], v[66:67]
	v_add_f32_e32 v65, 1.0, v65
	v_rcp_f32_e32 v66, v65
	v_mul_f32_e32 v65, 0x3d372713, v63
	v_mul_f32_e32 v65, v63, v65
	v_fma_f32 v65, v63, v65, v63
	v_mul_f32_e32 v65, 0x3f4c422a, v65
	v_mul_f32_e32 v65, 0xc038aa3b, v65
	v_exp_f32_e32 v65, v65
	v_cvt_pk_bf16_f32 v60, v60, v61
	v_add_f32_e32 v65, 1.0, v65
	v_rcp_f32_e32 v67, v65
	v_pk_mul_f32 v[56:57], v[56:57], v[64:65] op_sel_hi:[1,0]
	v_pk_mul_f32 v[58:59], v[58:59], v[64:65] op_sel_hi:[1,0]
	v_pk_mul_f32 v[52:53], v[52:53], v[64:65] op_sel_hi:[1,0]
	v_pk_mul_f32 v[62:63], v[62:63], v[66:67]
	v_pk_mul_f32 v[54:55], v[54:55], v[64:65] op_sel_hi:[1,0]
	v_cvt_pk_bf16_f32 v61, v62, v63
	v_mul_f32_e32 v62, 0x3d372713, v56
	v_mul_f32_e32 v63, 0x3d372713, v57
	v_mul_f32_e32 v62, v56, v62
	v_mul_f32_e32 v63, v57, v63
	v_fma_f32 v62, v56, v62, v56
	v_fma_f32 v63, v57, v63, v57
	v_mul_f32_e32 v62, 0x3f4c422a, v62
	v_mul_f32_e32 v63, 0x3f4c422a, v63
	v_mul_f32_e32 v62, 0xc038aa3b, v62
	v_mul_f32_e32 v63, 0xc038aa3b, v63
	v_exp_f32_e32 v62, v62
	v_exp_f32_e32 v63, v63
	v_pk_mul_f32 v[48:49], v[48:49], v[64:65] op_sel_hi:[1,0]
	v_pk_mul_f32 v[50:51], v[50:51], v[64:65] op_sel_hi:[1,0]
	v_add_f32_e32 v62, 1.0, v62
	v_add_f32_e32 v63, 1.0, v63
	v_rcp_f32_e32 v62, v62
	v_rcp_f32_e32 v63, v63
	s_nop 0
	v_pk_mul_f32 v[56:57], v[56:57], v[62:63]
	v_mul_f32_e32 v62, 0x3d372713, v58
	v_mul_f32_e32 v63, 0x3d372713, v59
	v_mul_f32_e32 v62, v58, v62
	v_mul_f32_e32 v63, v59, v63
	v_fma_f32 v62, v58, v62, v58
; DI unsigned pk2(float a, float b) { f32x2 v = {a, b}; bf16x2_t r = __builtin_convertvector(v, bf16x2_t); return __builtin_bit_cast(unsigned, r); }
;     DI void operator()(gacc_t& acc, int pm, int pn, char* lds, int tid, int wr, int wc, int lane) const {
;     ...
;         for (int m = 0; m < 8; ++m) {
;             const float r = rl[m * 16];
; #pragma unroll
;             for (int n = 0; n < 4; ++n) {
;                 float g[4];
; #pragma unroll
;                 for (int j = 0; j < 4; ++j) {
;                     const float x = acc[m][n][j] * r;
;                     const float u = 0.7978845608028654f * (x + 0.044715f * x * x * x);
;                     const float e = __builtin_amdgcn_exp2f(-2.885390081777927f * u);
;                     g[j] = x * __builtin_amdgcn_rcpf(1.0f + e);
;                 }
;                 u32x2 w; w.x = pk2(g[0], g[1]); w.y = pk2(g[2], g[3]);
;                 *(u32x2*)(lbase + m * 16 * 528 + n * 32) = w;
;             }
;             __builtin_amdgcn_sched_barrier(0);
	v_fma_f32 v63, v59, v63, v59
	v_mul_f32_e32 v62, 0x3f4c422a, v62
	v_mul_f32_e32 v63, 0x3f4c422a, v63
	v_mul_f32_e32 v62, 0xc038aa3b, v62
	v_mul_f32_e32 v63, 0xc038aa3b, v63
	v_exp_f32_e32 v62, v62
	v_exp_f32_e32 v63, v63
	v_cvt_pk_bf16_f32 v56, v56, v57
	v_add_f32_e32 v62, 1.0, v62
	v_add_f32_e32 v63, 1.0, v63
	v_rcp_f32_e32 v62, v62
	v_rcp_f32_e32 v63, v63
	s_nop 0
	v_pk_mul_f32 v[58:59], v[58:59], v[62:63]
	s_nop 0
	v_cvt_pk_bf16_f32 v57, v58, v59
	v_add_u32_e32 v58, 0x8000, v126
	ds_write2_b64 v58, v[60:61], v[56:57] offset0:128 offset1:132
	v_mul_f32_e32 v56, 0x3d372713, v52
	v_mul_f32_e32 v57, 0x3d372713, v53
	v_mul_f32_e32 v56, v52, v56
	v_mul_f32_e32 v57, v53, v57
	v_fma_f32 v56, v52, v56, v52
	v_fma_f32 v57, v53, v57, v53
	v_mul_f32_e32 v56, 0x3f4c422a, v56
	v_mul_f32_e32 v57, 0x3f4c422a, v57
	v_mul_f32_e32 v56, 0xc038aa3b, v56
	v_mul_f32_e32 v57, 0xc038aa3b, v57
	v_exp_f32_e32 v56, v56
	v_exp_f32_e32 v57, v57
	v_add_f32_e32 v56, 1.0, v56
	v_add_f32_e32 v57, 1.0, v57
	v_rcp_f32_e32 v56, v56
	v_rcp_f32_e32 v57, v57
	s_nop 0
	v_pk_mul_f32 v[52:53], v[52:53], v[56:57]
	v_mul_f32_e32 v56, 0x3d372713, v54
	v_mul_f32_e32 v57, 0x3d372713, v55
	v_mul_f32_e32 v56, v54, v56
	v_mul_f32_e32 v57, v55, v57
	v_fma_f32 v56, v54, v56, v54
	v_fma_f32 v57, v55, v57, v55
	v_mul_f32_e32 v56, 0x3f4c422a, v56
	v_mul_f32_e32 v57, 0x3f4c422a, v57
	v_mul_f32_e32 v56, 0xc038aa3b, v56
	v_mul_f32_e32 v57, 0xc038aa3b, v57
	v_exp_f32_e32 v56, v56
	v_exp_f32_e32 v57, v57
	v_cvt_pk_bf16_f32 v52, v52, v53
	v_add_f32_e32 v56, 1.0, v56
	v_add_f32_e32 v57, 1.0, v57
	v_rcp_f32_e32 v56, v56
	v_rcp_f32_e32 v57, v57
	s_nop 0
	v_pk_mul_f32 v[54:55], v[54:55], v[56:57]
	s_nop 0
	v_cvt_pk_bf16_f32 v53, v54, v55
	v_mul_f32_e32 v54, 0x3d372713, v48
	v_mul_f32_e32 v55, 0x3d372713, v49
	v_mul_f32_e32 v54, v48, v54
	v_mul_f32_e32 v55, v49, v55
	v_fma_f32 v54, v48, v54, v48
	v_fma_f32 v55, v49, v55, v49
	v_mul_f32_e32 v54, 0x3f4c422a, v54
	v_mul_f32_e32 v55, 0x3f4c422a, v55
	v_mul_f32_e32 v54, 0xc038aa3b, v54
	v_mul_f32_e32 v55, 0xc038aa3b, v55
	v_exp_f32_e32 v54, v54
	v_exp_f32_e32 v55, v55
	v_add_f32_e32 v54, 1.0, v54
	v_add_f32_e32 v55, 1.0, v55
	v_rcp_f32_e32 v54, v54
	v_rcp_f32_e32 v55, v55
	s_nop 0
	v_pk_mul_f32 v[48:49], v[48:49], v[54:55]
	v_mul_f32_e32 v54, 0x3d372713, v50
	v_mul_f32_e32 v55, 0x3d372713, v51
	v_mul_f32_e32 v54, v50, v54
	v_mul_f32_e32 v55, v51, v55
	v_fma_f32 v54, v50, v54, v50
	v_fma_f32 v55, v51, v55, v51
	v_mul_f32_e32 v54, 0x3f4c422a, v54
	v_mul_f32_e32 v55, 0x3f4c422a, v55
	v_mul_f32_e32 v54, 0xc038aa3b, v54
	v_mul_f32_e32 v55, 0xc038aa3b, v55
	v_exp_f32_e32 v54, v54
	v_exp_f32_e32 v55, v55
	v_cvt_pk_bf16_f32 v48, v48, v49
	v_add_f32_e32 v54, 1.0, v54
	v_add_f32_e32 v55, 1.0, v55
	v_rcp_f32_e32 v54, v54
	v_rcp_f32_e32 v55, v55
	s_nop 0
	v_pk_mul_f32 v[50:51], v[50:51], v[54:55]
	s_nop 0
	v_cvt_pk_bf16_f32 v49, v50, v51
	ds_write2_b64 v58, v[52:53], v[48:49] offset0:136 offset1:140
	v_mov_b32_e32 v48, v249
	v_pk_mul_f32 v[44:45], v[44:45], v[48:49] op_sel_hi:[1,0]
	s_nop 0
	v_mul_f32_e32 v49, 0x3d372713, v44
	v_mul_f32_e32 v49, v44, v49
	v_fma_f32 v49, v44, v49, v44
	v_mul_f32_e32 v49, 0x3f4c422a, v49
	v_mul_f32_e32 v49, 0xc038aa3b, v49
	v_exp_f32_e32 v49, v49
	s_nop 0
	v_add_f32_e32 v49, 1.0, v49
	v_rcp_f32_e32 v50, v49
	v_mul_f32_e32 v49, 0x3d372713, v45
	v_mul_f32_e32 v49, v45, v49
	v_fma_f32 v49, v45, v49, v45
	v_mul_f32_e32 v49, 0x3f4c422a, v49
	v_mul_f32_e32 v49, 0xc038aa3b, v49
	v_exp_f32_e32 v49, v49
	s_nop 0
	v_add_f32_e32 v49, 1.0, v49
	v_pk_mul_f32 v[46:47], v[46:47], v[48:49] op_sel_hi:[1,0]
	v_rcp_f32_e32 v51, v49
	v_mul_f32_e32 v49, 0x3d372713, v46
	v_mul_f32_e32 v49, v46, v49
	v_fma_f32 v49, v46, v49, v46
	v_mul_f32_e32 v49, 0x3f4c422a, v49
	v_mul_f32_e32 v49, 0xc038aa3b, v49
	v_exp_f32_e32 v49, v49
	v_pk_mul_f32 v[44:45], v[44:45], v[50:51]
	v_add_f32_e32 v49, 1.0, v49
	v_rcp_f32_e32 v50, v49
	v_mul_f32_e32 v49, 0x3d372713, v47
	v_mul_f32_e32 v49, v47, v49
	v_fma_f32 v49, v47, v49, v47
	v_mul_f32_e32 v49, 0x3f4c422a, v49
	v_mul_f32_e32 v49, 0xc038aa3b, v49
	v_exp_f32_e32 v49, v49
	v_cvt_pk_bf16_f32 v44, v44, v45
	v_add_f32_e32 v49, 1.0, v49
	v_rcp_f32_e32 v51, v49
	v_pk_mul_f32 v[40:41], v[40:41], v[48:49] op_sel_hi:[1,0]
	v_pk_mul_f32 v[42:43], v[42:43], v[48:49] op_sel_hi:[1,0]
	v_pk_mul_f32 v[36:37], v[36:37], v[48:49] op_sel_hi:[1,0]
	v_pk_mul_f32 v[46:47], v[46:47], v[50:51]
	v_pk_mul_f32 v[38:39], v[38:39], v[48:49] op_sel_hi:[1,0]
	v_cvt_pk_bf16_f32 v45, v46, v47
	v_mul_f32_e32 v46, 0x3d372713, v40
	v_mul_f32_e32 v47, 0x3d372713, v41
	v_mul_f32_e32 v46, v40, v46
	v_mul_f32_e32 v47, v41, v47
	v_fma_f32 v46, v40, v46, v40
	v_fma_f32 v47, v41, v47, v41
	v_mul_f32_e32 v46, 0x3f4c422a, v46
	v_mul_f32_e32 v47, 0x3f4c422a, v47
	v_mul_f32_e32 v46, 0xc038aa3b, v46
	v_mul_f32_e32 v47, 0xc038aa3b, v47
	v_exp_f32_e32 v46, v46
	v_exp_f32_e32 v47, v47
	v_pk_mul_f32 v[32:33], v[32:33], v[48:49] op_sel_hi:[1,0]
	v_pk_mul_f32 v[34:35], v[34:35], v[48:49] op_sel_hi:[1,0]
	v_add_f32_e32 v46, 1.0, v46
	v_add_f32_e32 v47, 1.0, v47
	v_rcp_f32_e32 v46, v46
	v_rcp_f32_e32 v47, v47
	s_nop 0
	v_pk_mul_f32 v[40:41], v[40:41], v[46:47]
	v_mul_f32_e32 v46, 0x3d372713, v42
	v_mul_f32_e32 v47, 0x3d372713, v43
	v_mul_f32_e32 v46, v42, v46
	v_mul_f32_e32 v47, v43, v47
	v_fma_f32 v46, v42, v46, v42
	v_fma_f32 v47, v43, v47, v43
	v_mul_f32_e32 v46, 0x3f4c422a, v46
	v_mul_f32_e32 v47, 0x3f4c422a, v47
	v_mul_f32_e32 v46, 0xc038aa3b, v46
	v_mul_f32_e32 v47, 0xc038aa3b, v47
	v_exp_f32_e32 v46, v46
	v_exp_f32_e32 v47, v47
	v_cvt_pk_bf16_f32 v40, v40, v41
	v_add_f32_e32 v46, 1.0, v46
	v_add_f32_e32 v47, 1.0, v47
	v_rcp_f32_e32 v46, v46
	v_rcp_f32_e32 v47, v47
; DI unsigned pk2(float a, float b) { f32x2 v = {a, b}; bf16x2_t r = __builtin_convertvector(v, bf16x2_t); return __builtin_bit_cast(unsigned, r); }
;     DI void operator()(gacc_t& acc, int pm, int pn, char* lds, int tid, int wr, int wc, int lane) const {
;     ...
;         for (int m = 0; m < 8; ++m) {
;             const float r = rl[m * 16];
; #pragma unroll
;             for (int n = 0; n < 4; ++n) {
;                 float g[4];
; #pragma unroll
;                 for (int j = 0; j < 4; ++j) {
;                     const float x = acc[m][n][j] * r;
;                     const float u = 0.7978845608028654f * (x + 0.044715f * x * x * x);
;                     const float e = __builtin_amdgcn_exp2f(-2.885390081777927f * u);
;                     g[j] = x * __builtin_amdgcn_rcpf(1.0f + e);
;                 }
;                 u32x2 w; w.x = pk2(g[0], g[1]); w.y = pk2(g[2], g[3]);
;                 *(u32x2*)(lbase + m * 16 * 528 + n * 32) = w;
;             }
;             __builtin_amdgcn_sched_barrier(0);
	s_nop 0
	v_pk_mul_f32 v[42:43], v[42:43], v[46:47]
	s_nop 0
	v_cvt_pk_bf16_f32 v41, v42, v43
	v_add_u32_e32 v42, 0xa000, v126
	ds_write2_b64 v42, v[44:45], v[40:41] offset0:160 offset1:164
	v_mul_f32_e32 v40, 0x3d372713, v36
	v_mul_f32_e32 v41, 0x3d372713, v37
	v_mul_f32_e32 v40, v36, v40
	v_mul_f32_e32 v41, v37, v41
	v_fma_f32 v40, v36, v40, v36
	v_fma_f32 v41, v37, v41, v37
	v_mul_f32_e32 v40, 0x3f4c422a, v40
	v_mul_f32_e32 v41, 0x3f4c422a, v41
	v_mul_f32_e32 v40, 0xc038aa3b, v40
	v_mul_f32_e32 v41, 0xc038aa3b, v41
	v_exp_f32_e32 v40, v40
	v_exp_f32_e32 v41, v41
	v_add_f32_e32 v40, 1.0, v40
	v_add_f32_e32 v41, 1.0, v41
	v_rcp_f32_e32 v40, v40
	v_rcp_f32_e32 v41, v41
	s_nop 0
	v_pk_mul_f32 v[36:37], v[36:37], v[40:41]
	v_mul_f32_e32 v40, 0x3d372713, v38
	v_mul_f32_e32 v41, 0x3d372713, v39
	v_mul_f32_e32 v40, v38, v40
	v_mul_f32_e32 v41, v39, v41
	v_fma_f32 v40, v38, v40, v38
	v_fma_f32 v41, v39, v41, v39
	v_mul_f32_e32 v40, 0x3f4c422a, v40
	v_mul_f32_e32 v41, 0x3f4c422a, v41
	v_mul_f32_e32 v40, 0xc038aa3b, v40
	v_mul_f32_e32 v41, 0xc038aa3b, v41
	v_exp_f32_e32 v40, v40
	v_exp_f32_e32 v41, v41
	v_cvt_pk_bf16_f32 v36, v36, v37
	v_add_f32_e32 v40, 1.0, v40
	v_add_f32_e32 v41, 1.0, v41
	v_rcp_f32_e32 v40, v40
	v_rcp_f32_e32 v41, v41
	s_nop 0
	v_pk_mul_f32 v[38:39], v[38:39], v[40:41]
	s_nop 0
	v_cvt_pk_bf16_f32 v37, v38, v39
	v_mul_f32_e32 v38, 0x3d372713, v32
	v_mul_f32_e32 v39, 0x3d372713, v33
	v_mul_f32_e32 v38, v32, v38
	v_mul_f32_e32 v39, v33, v39
	v_fma_f32 v38, v32, v38, v32
	v_fma_f32 v39, v33, v39, v33
	v_mul_f32_e32 v38, 0x3f4c422a, v38
	v_mul_f32_e32 v39, 0x3f4c422a, v39
	v_mul_f32_e32 v38, 0xc038aa3b, v38
	v_mul_f32_e32 v39, 0xc038aa3b, v39
	v_exp_f32_e32 v38, v38
	v_exp_f32_e32 v39, v39
	v_add_f32_e32 v38, 1.0, v38
	v_add_f32_e32 v39, 1.0, v39
	v_rcp_f32_e32 v38, v38
	v_rcp_f32_e32 v39, v39
	s_nop 0
	v_pk_mul_f32 v[32:33], v[32:33], v[38:39]
	v_mul_f32_e32 v38, 0x3d372713, v34
	v_mul_f32_e32 v39, 0x3d372713, v35
	v_mul_f32_e32 v38, v34, v38
	v_mul_f32_e32 v39, v35, v39
	v_fma_f32 v38, v34, v38, v34
	v_fma_f32 v39, v35, v39, v35
	v_mul_f32_e32 v38, 0x3f4c422a, v38
	v_mul_f32_e32 v39, 0x3f4c422a, v39
	v_mul_f32_e32 v38, 0xc038aa3b, v38
	v_mul_f32_e32 v39, 0xc038aa3b, v39
	v_exp_f32_e32 v38, v38
	v_exp_f32_e32 v39, v39
	v_cvt_pk_bf16_f32 v32, v32, v33
	v_add_f32_e32 v38, 1.0, v38
	v_add_f32_e32 v39, 1.0, v39
	v_rcp_f32_e32 v38, v38
	v_rcp_f32_e32 v39, v39
	s_nop 0
	v_pk_mul_f32 v[34:35], v[34:35], v[38:39]
	s_nop 0
	v_cvt_pk_bf16_f32 v33, v34, v35
	ds_write2_b64 v42, v[36:37], v[32:33] offset0:168 offset1:172
	v_mov_b32_e32 v32, v250
	v_pk_mul_f32 v[28:29], v[28:29], v[32:33] op_sel_hi:[1,0]
	s_nop 0
	v_mul_f32_e32 v33, 0x3d372713, v28
	v_mul_f32_e32 v33, v28, v33
	v_fma_f32 v33, v28, v33, v28
	v_mul_f32_e32 v33, 0x3f4c422a, v33
	v_mul_f32_e32 v33, 0xc038aa3b, v33
	v_exp_f32_e32 v33, v33
	s_nop 0
	v_add_f32_e32 v33, 1.0, v33
	v_rcp_f32_e32 v34, v33
	v_mul_f32_e32 v33, 0x3d372713, v29
	v_mul_f32_e32 v33, v29, v33
	v_fma_f32 v33, v29, v33, v29
	v_mul_f32_e32 v33, 0x3f4c422a, v33
	v_mul_f32_e32 v33, 0xc038aa3b, v33
	v_exp_f32_e32 v33, v33
	s_nop 0
	v_add_f32_e32 v33, 1.0, v33
	v_pk_mul_f32 v[30:31], v[30:31], v[32:33] op_sel_hi:[1,0]
	v_rcp_f32_e32 v35, v33
	v_mul_f32_e32 v33, 0x3d372713, v30
	v_mul_f32_e32 v33, v30, v33
	v_fma_f32 v33, v30, v33, v30
	v_mul_f32_e32 v33, 0x3f4c422a, v33
	v_mul_f32_e32 v33, 0xc038aa3b, v33
	v_exp_f32_e32 v33, v33
	v_pk_mul_f32 v[28:29], v[28:29], v[34:35]
	v_add_f32_e32 v33, 1.0, v33
	v_rcp_f32_e32 v34, v33
	v_mul_f32_e32 v33, 0x3d372713, v31
	v_mul_f32_e32 v33, v31, v33
	v_fma_f32 v33, v31, v33, v31
	v_mul_f32_e32 v33, 0x3f4c422a, v33
	v_mul_f32_e32 v33, 0xc038aa3b, v33
	v_exp_f32_e32 v33, v33
	v_cvt_pk_bf16_f32 v28, v28, v29
	v_add_f32_e32 v33, 1.0, v33
	v_rcp_f32_e32 v35, v33
	v_pk_mul_f32 v[24:25], v[24:25], v[32:33] op_sel_hi:[1,0]
	v_pk_mul_f32 v[26:27], v[26:27], v[32:33] op_sel_hi:[1,0]
	v_pk_mul_f32 v[20:21], v[20:21], v[32:33] op_sel_hi:[1,0]
	v_pk_mul_f32 v[30:31], v[30:31], v[34:35]
	v_pk_mul_f32 v[22:23], v[22:23], v[32:33] op_sel_hi:[1,0]
	v_cvt_pk_bf16_f32 v29, v30, v31
	v_mul_f32_e32 v30, 0x3d372713, v24
	v_mul_f32_e32 v31, 0x3d372713, v25
	v_mul_f32_e32 v30, v24, v30
	v_mul_f32_e32 v31, v25, v31
	v_fma_f32 v30, v24, v30, v24
	v_fma_f32 v31, v25, v31, v25
	v_mul_f32_e32 v30, 0x3f4c422a, v30
	v_mul_f32_e32 v31, 0x3f4c422a, v31
	v_mul_f32_e32 v30, 0xc038aa3b, v30
	v_mul_f32_e32 v31, 0xc038aa3b, v31
	v_exp_f32_e32 v30, v30
	v_exp_f32_e32 v31, v31
	v_pk_mul_f32 v[16:17], v[16:17], v[32:33] op_sel_hi:[1,0]
	v_pk_mul_f32 v[18:19], v[18:19], v[32:33] op_sel_hi:[1,0]
	v_add_f32_e32 v30, 1.0, v30
	v_add_f32_e32 v31, 1.0, v31
	v_rcp_f32_e32 v30, v30
	v_rcp_f32_e32 v31, v31
	s_nop 0
	v_pk_mul_f32 v[24:25], v[24:25], v[30:31]
	v_mul_f32_e32 v30, 0x3d372713, v26
	v_mul_f32_e32 v31, 0x3d372713, v27
	v_mul_f32_e32 v30, v26, v30
	v_mul_f32_e32 v31, v27, v31
	v_fma_f32 v30, v26, v30, v26
	v_fma_f32 v31, v27, v31, v27
	v_mul_f32_e32 v30, 0x3f4c422a, v30
	v_mul_f32_e32 v31, 0x3f4c422a, v31
	v_mul_f32_e32 v30, 0xc038aa3b, v30
	v_mul_f32_e32 v31, 0xc038aa3b, v31
	v_exp_f32_e32 v30, v30
	v_exp_f32_e32 v31, v31
	v_cvt_pk_bf16_f32 v24, v24, v25
	v_add_f32_e32 v30, 1.0, v30
	v_add_f32_e32 v31, 1.0, v31
	v_rcp_f32_e32 v30, v30
	v_rcp_f32_e32 v31, v31
	s_nop 0
	v_pk_mul_f32 v[26:27], v[26:27], v[30:31]
	s_nop 0
	v_cvt_pk_bf16_f32 v25, v26, v27
	v_add_u32_e32 v26, 0xc000, v126
	ds_write2_b64 v26, v[28:29], v[24:25] offset0:192 offset1:196
	v_mul_f32_e32 v24, 0x3d372713, v20
	v_mul_f32_e32 v25, 0x3d372713, v21
	v_mul_f32_e32 v24, v20, v24
	v_mul_f32_e32 v25, v21, v25
	v_fma_f32 v24, v20, v24, v20
; DI unsigned pk2(float a, float b) { f32x2 v = {a, b}; bf16x2_t r = __builtin_convertvector(v, bf16x2_t); return __builtin_bit_cast(unsigned, r); }
;     DI void operator()(gacc_t& acc, int pm, int pn, char* lds, int tid, int wr, int wc, int lane) const {
;     ...
;         for (int m = 0; m < 8; ++m) {
;             const float r = rl[m * 16];
; #pragma unroll
;             for (int n = 0; n < 4; ++n) {
;                 float g[4];
; #pragma unroll
;                 for (int j = 0; j < 4; ++j) {
;                     const float x = acc[m][n][j] * r;
;                     const float u = 0.7978845608028654f * (x + 0.044715f * x * x * x);
;                     const float e = __builtin_amdgcn_exp2f(-2.885390081777927f * u);
;                     g[j] = x * __builtin_amdgcn_rcpf(1.0f + e);
;                 }
;                 u32x2 w; w.x = pk2(g[0], g[1]); w.y = pk2(g[2], g[3]);
;                 *(u32x2*)(lbase + m * 16 * 528 + n * 32) = w;
;             }
;             __builtin_amdgcn_sched_barrier(0);
	v_fma_f32 v25, v21, v25, v21
	v_mul_f32_e32 v24, 0x3f4c422a, v24
	v_mul_f32_e32 v25, 0x3f4c422a, v25
	v_mul_f32_e32 v24, 0xc038aa3b, v24
	v_mul_f32_e32 v25, 0xc038aa3b, v25
	v_exp_f32_e32 v24, v24
	v_exp_f32_e32 v25, v25
	v_add_f32_e32 v24, 1.0, v24
	v_add_f32_e32 v25, 1.0, v25
	v_rcp_f32_e32 v24, v24
	v_rcp_f32_e32 v25, v25
	s_nop 0
	v_pk_mul_f32 v[20:21], v[20:21], v[24:25]
	v_mul_f32_e32 v24, 0x3d372713, v22
	v_mul_f32_e32 v25, 0x3d372713, v23
	v_mul_f32_e32 v24, v22, v24
	v_mul_f32_e32 v25, v23, v25
	v_fma_f32 v24, v22, v24, v22
	v_fma_f32 v25, v23, v25, v23
	v_mul_f32_e32 v24, 0x3f4c422a, v24
	v_mul_f32_e32 v25, 0x3f4c422a, v25
	v_mul_f32_e32 v24, 0xc038aa3b, v24
	v_mul_f32_e32 v25, 0xc038aa3b, v25
	v_exp_f32_e32 v24, v24
	v_exp_f32_e32 v25, v25
	v_cvt_pk_bf16_f32 v20, v20, v21
	v_add_f32_e32 v24, 1.0, v24
	v_add_f32_e32 v25, 1.0, v25
	v_rcp_f32_e32 v24, v24
	v_rcp_f32_e32 v25, v25
	s_nop 0
	v_pk_mul_f32 v[22:23], v[22:23], v[24:25]
	s_nop 0
	v_cvt_pk_bf16_f32 v21, v22, v23
	v_mul_f32_e32 v22, 0x3d372713, v16
	v_mul_f32_e32 v23, 0x3d372713, v17
	v_mul_f32_e32 v22, v16, v22
	v_mul_f32_e32 v23, v17, v23
	v_fma_f32 v22, v16, v22, v16
	v_fma_f32 v23, v17, v23, v17
	v_mul_f32_e32 v22, 0x3f4c422a, v22
	v_mul_f32_e32 v23, 0x3f4c422a, v23
	v_mul_f32_e32 v22, 0xc038aa3b, v22
	v_mul_f32_e32 v23, 0xc038aa3b, v23
	v_exp_f32_e32 v22, v22
	v_exp_f32_e32 v23, v23
	v_add_f32_e32 v22, 1.0, v22
	v_add_f32_e32 v23, 1.0, v23
	v_rcp_f32_e32 v22, v22
	v_rcp_f32_e32 v23, v23
	s_nop 0
	v_pk_mul_f32 v[16:17], v[16:17], v[22:23]
	v_mul_f32_e32 v22, 0x3d372713, v18
	v_mul_f32_e32 v23, 0x3d372713, v19
	v_mul_f32_e32 v22, v18, v22
	v_mul_f32_e32 v23, v19, v23
	v_fma_f32 v22, v18, v22, v18
	v_fma_f32 v23, v19, v23, v19
	v_mul_f32_e32 v22, 0x3f4c422a, v22
	v_mul_f32_e32 v23, 0x3f4c422a, v23
	v_mul_f32_e32 v22, 0xc038aa3b, v22
	v_mul_f32_e32 v23, 0xc038aa3b, v23
	v_exp_f32_e32 v22, v22
	v_exp_f32_e32 v23, v23
	v_cvt_pk_bf16_f32 v16, v16, v17
	v_add_f32_e32 v22, 1.0, v22
	v_add_f32_e32 v23, 1.0, v23
	v_rcp_f32_e32 v22, v22
	v_rcp_f32_e32 v23, v23
	s_nop 0
	v_pk_mul_f32 v[18:19], v[18:19], v[22:23]
	s_nop 0
	v_cvt_pk_bf16_f32 v17, v18, v19
	ds_write2_b64 v26, v[20:21], v[16:17] offset0:200 offset1:204
	v_mov_b32_e32 v16, v251
	v_pk_mul_f32 v[12:13], v[12:13], v[16:17] op_sel_hi:[1,0]
	s_nop 0
	v_mul_f32_e32 v17, 0x3d372713, v12
	v_mul_f32_e32 v17, v12, v17
	v_fma_f32 v17, v12, v17, v12
	v_mul_f32_e32 v17, 0x3f4c422a, v17
	v_mul_f32_e32 v17, 0xc038aa3b, v17
	v_exp_f32_e32 v17, v17
	s_nop 0
	v_add_f32_e32 v17, 1.0, v17
	v_rcp_f32_e32 v18, v17
	v_mul_f32_e32 v17, 0x3d372713, v13
	v_mul_f32_e32 v17, v13, v17
	v_fma_f32 v17, v13, v17, v13
	v_mul_f32_e32 v17, 0x3f4c422a, v17
	v_mul_f32_e32 v17, 0xc038aa3b, v17
	v_exp_f32_e32 v17, v17
	s_nop 0
	v_add_f32_e32 v17, 1.0, v17
	v_pk_mul_f32 v[14:15], v[14:15], v[16:17] op_sel_hi:[1,0]
	v_rcp_f32_e32 v19, v17
	v_mul_f32_e32 v17, 0x3d372713, v14
	v_mul_f32_e32 v17, v14, v17
	v_fma_f32 v17, v14, v17, v14
	v_mul_f32_e32 v17, 0x3f4c422a, v17
	v_mul_f32_e32 v17, 0xc038aa3b, v17
	v_exp_f32_e32 v17, v17
	v_pk_mul_f32 v[12:13], v[12:13], v[18:19]
	v_add_f32_e32 v17, 1.0, v17
	v_rcp_f32_e32 v18, v17
	v_mul_f32_e32 v17, 0x3d372713, v15
	v_mul_f32_e32 v17, v15, v17
	v_fma_f32 v17, v15, v17, v15
	v_mul_f32_e32 v17, 0x3f4c422a, v17
	v_mul_f32_e32 v17, 0xc038aa3b, v17
	v_exp_f32_e32 v17, v17
	v_cvt_pk_bf16_f32 v12, v12, v13
	v_add_f32_e32 v17, 1.0, v17
	v_rcp_f32_e32 v19, v17
	v_pk_mul_f32 v[8:9], v[8:9], v[16:17] op_sel_hi:[1,0]
	v_pk_mul_f32 v[10:11], v[10:11], v[16:17] op_sel_hi:[1,0]
	v_pk_mul_f32 v[4:5], v[4:5], v[16:17] op_sel_hi:[1,0]
	v_pk_mul_f32 v[14:15], v[14:15], v[18:19]
	v_pk_mul_f32 v[6:7], v[6:7], v[16:17] op_sel_hi:[1,0]
	v_cvt_pk_bf16_f32 v13, v14, v15
	v_mul_f32_e32 v14, 0x3d372713, v8
	v_mul_f32_e32 v15, 0x3d372713, v9
	v_mul_f32_e32 v14, v8, v14
	v_mul_f32_e32 v15, v9, v15
	v_fma_f32 v14, v8, v14, v8
	v_fma_f32 v15, v9, v15, v9
	v_mul_f32_e32 v14, 0x3f4c422a, v14
	v_mul_f32_e32 v15, 0x3f4c422a, v15
	v_mul_f32_e32 v14, 0xc038aa3b, v14
	v_mul_f32_e32 v15, 0xc038aa3b, v15
	v_exp_f32_e32 v14, v14
	v_exp_f32_e32 v15, v15
	v_pk_mul_f32 v[0:1], v[0:1], v[16:17] op_sel_hi:[1,0]
	v_pk_mul_f32 v[2:3], v[2:3], v[16:17] op_sel_hi:[1,0]
	v_add_f32_e32 v14, 1.0, v14
	v_add_f32_e32 v15, 1.0, v15
	v_rcp_f32_e32 v14, v14
	v_rcp_f32_e32 v15, v15
	s_nop 0
	v_pk_mul_f32 v[8:9], v[8:9], v[14:15]
	v_mul_f32_e32 v14, 0x3d372713, v10
	v_mul_f32_e32 v15, 0x3d372713, v11
	v_mul_f32_e32 v14, v10, v14
	v_mul_f32_e32 v15, v11, v15
	v_fma_f32 v14, v10, v14, v10
	v_fma_f32 v15, v11, v15, v11
	v_mul_f32_e32 v14, 0x3f4c422a, v14
	v_mul_f32_e32 v15, 0x3f4c422a, v15
	v_mul_f32_e32 v14, 0xc038aa3b, v14
	v_mul_f32_e32 v15, 0xc038aa3b, v15
	v_exp_f32_e32 v14, v14
	v_exp_f32_e32 v15, v15
	v_cvt_pk_bf16_f32 v8, v8, v9
	v_add_f32_e32 v14, 1.0, v14
	v_add_f32_e32 v15, 1.0, v15
	v_rcp_f32_e32 v14, v14
	v_rcp_f32_e32 v15, v15
	s_nop 0
	v_pk_mul_f32 v[10:11], v[10:11], v[14:15]
	s_nop 0
	v_cvt_pk_bf16_f32 v9, v10, v11
	v_add_u32_e32 v10, 0xe000, v126
	ds_write2_b64 v10, v[12:13], v[8:9] offset0:224 offset1:228
	v_mul_f32_e32 v8, 0x3d372713, v4
	v_mul_f32_e32 v9, 0x3d372713, v5
	v_mul_f32_e32 v8, v4, v8
	v_mul_f32_e32 v9, v5, v9
	v_fma_f32 v8, v4, v8, v4
	v_fma_f32 v9, v5, v9, v5
	v_mul_f32_e32 v8, 0x3f4c422a, v8
	v_mul_f32_e32 v9, 0x3f4c422a, v9
	v_mul_f32_e32 v8, 0xc038aa3b, v8
	v_mul_f32_e32 v9, 0xc038aa3b, v9
	v_exp_f32_e32 v8, v8
	v_exp_f32_e32 v9, v9
	v_add_f32_e32 v8, 1.0, v8
	v_add_f32_e32 v9, 1.0, v9
	v_rcp_f32_e32 v8, v8
	v_rcp_f32_e32 v9, v9
	s_nop 0
	v_pk_mul_f32 v[4:5], v[4:5], v[8:9]
	v_mul_f32_e32 v8, 0x3d372713, v6
	v_mul_f32_e32 v9, 0x3d372713, v7
; DI unsigned pk2(float a, float b) { f32x2 v = {a, b}; bf16x2_t r = __builtin_convertvector(v, bf16x2_t); return __builtin_bit_cast(unsigned, r); }
; DI void store_tile_from_lds(const char* lds, bf16_t* dst, long ld, int tid) {
;     ...
;     for (int k = 0; k < 16; ++k) {
;         const int id = tid + NTH * k, row = id >> 5, ch = id & 31;
;         const u32x4 v = *(const u32x4*)(lds + row * 528 + ch * 16);
;         *(u32x4*)(dst + (long)row * ld + ch * 8) = v;
;     DI void operator()(gacc_t& acc, int pm, int pn, char* lds, int tid, int wr, int wc, int lane) const {
;     ...
;                 u32x2 w; w.x = pk2(g[0], g[1]); w.y = pk2(g[2], g[3]);
;                 *(u32x2*)(lbase + m * 16 * 528 + n * 32) = w;
;             }
;             __builtin_amdgcn_sched_barrier(0);
;         }
;         __syncthreads();
;         store_tile_from_lds(lds, z + (long)pm * 256 * 2048 + pn * 256, 2048, tid);
;         __syncthreads();
	v_mul_f32_e32 v8, v6, v8
	v_mul_f32_e32 v9, v7, v9
	v_fma_f32 v8, v6, v8, v6
	v_fma_f32 v9, v7, v9, v7
	v_mul_f32_e32 v8, 0x3f4c422a, v8
	v_mul_f32_e32 v9, 0x3f4c422a, v9
	v_mul_f32_e32 v8, 0xc038aa3b, v8
	v_mul_f32_e32 v9, 0xc038aa3b, v9
	v_exp_f32_e32 v8, v8
	v_exp_f32_e32 v9, v9
	v_cvt_pk_bf16_f32 v4, v4, v5
	v_add_f32_e32 v8, 1.0, v8
	v_add_f32_e32 v9, 1.0, v9
	v_rcp_f32_e32 v8, v8
	v_rcp_f32_e32 v9, v9
	s_nop 0
	v_pk_mul_f32 v[6:7], v[6:7], v[8:9]
	s_nop 0
	v_cvt_pk_bf16_f32 v5, v6, v7
	v_mul_f32_e32 v6, 0x3d372713, v0
	v_mul_f32_e32 v7, 0x3d372713, v1
	v_mul_f32_e32 v6, v0, v6
	v_mul_f32_e32 v7, v1, v7
	v_fma_f32 v6, v0, v6, v0
	v_fma_f32 v7, v1, v7, v1
	v_mul_f32_e32 v6, 0x3f4c422a, v6
	v_mul_f32_e32 v7, 0x3f4c422a, v7
	v_mul_f32_e32 v6, 0xc038aa3b, v6
	v_mul_f32_e32 v7, 0xc038aa3b, v7
	v_exp_f32_e32 v6, v6
	v_exp_f32_e32 v7, v7
	v_add_f32_e32 v6, 1.0, v6
	v_add_f32_e32 v7, 1.0, v7
	v_rcp_f32_e32 v6, v6
	v_rcp_f32_e32 v7, v7
	s_nop 0
	v_pk_mul_f32 v[0:1], v[0:1], v[6:7]
	v_mul_f32_e32 v6, 0x3d372713, v2
	v_mul_f32_e32 v7, 0x3d372713, v3
	v_mul_f32_e32 v6, v2, v6
	v_mul_f32_e32 v7, v3, v7
	v_fma_f32 v6, v2, v6, v2
	v_fma_f32 v7, v3, v7, v3
	v_mul_f32_e32 v6, 0x3f4c422a, v6
	v_mul_f32_e32 v7, 0x3f4c422a, v7
	v_mul_f32_e32 v6, 0xc038aa3b, v6
	v_mul_f32_e32 v7, 0xc038aa3b, v7
	v_exp_f32_e32 v6, v6
	v_exp_f32_e32 v7, v7
	v_cvt_pk_bf16_f32 v0, v0, v1
	v_add_f32_e32 v6, 1.0, v6
	v_add_f32_e32 v7, 1.0, v7
	v_rcp_f32_e32 v6, v6
	v_rcp_f32_e32 v7, v7
	s_nop 0
	v_pk_mul_f32 v[2:3], v[2:3], v[6:7]
	s_nop 0
	v_cvt_pk_bf16_f32 v1, v2, v3
	ds_write2_b64 v10, v[4:5], v[0:1] offset0:232 offset1:236
	s_lshl_b64 s[8:9], s[8:9], 20
	s_add_u32 s8, s70, s8
	s_addc_u32 s9, s71, s9
	s_lshl_b32 s6, s6, 8
	s_ashr_i32 s7, s6, 31
	v_lshlrev_b32_e32 v0, 4, v125
	s_lshl_b64 s[6:7], s[6:7], 1
	v_and_b32_e32 v146, 0x1f0, v0
	s_add_u32 s6, s8, s6
	v_add_u32_e32 v4, 0, v146
	v_ashrrev_i32_e32 v6, 5, v125
	s_addc_u32 s7, s9, s7
	v_mad_u64_u32 v[0:1], s[8:9], v6, s3, v[4:5]
	s_waitcnt lgkmcnt(0)
	s_barrier
	ds_read_b128 v[0:3], v0
	v_ashrrev_i32_e32 v7, 31, v6
	v_lshl_add_u64 v[8:9], s[6:7], 0, v[146:147]
	v_lshlrev_b64 v[6:7], 12, v[6:7]
	v_lshl_add_u64 v[6:7], v[8:9], 0, v[6:7]
	s_waitcnt lgkmcnt(0)
	flat_store_dwordx4 v[6:7], v[0:3]
	s_add_i32 s17, s17, 1
	s_nop 0
	v_add_u32_e32 v0, 0x200, v125
	v_ashrrev_i32_e32 v6, 5, v0
	v_mad_u64_u32 v[0:1], s[6:7], v6, s3, v[4:5]
	ds_read_b128 v[0:3], v0
	v_ashrrev_i32_e32 v7, 31, v6
	v_lshlrev_b64 v[6:7], 12, v[6:7]
	v_lshl_add_u64 v[6:7], v[8:9], 0, v[6:7]
	s_waitcnt lgkmcnt(0)
	flat_store_dwordx4 v[6:7], v[0:3]
	s_nop 1
	v_add_u32_e32 v0, 0x400, v125
	v_ashrrev_i32_e32 v6, 5, v0
	v_mad_u64_u32 v[0:1], s[6:7], v6, s3, v[4:5]
	ds_read_b128 v[0:3], v0
	v_ashrrev_i32_e32 v7, 31, v6
	v_lshlrev_b64 v[6:7], 12, v[6:7]
	v_lshl_add_u64 v[6:7], v[8:9], 0, v[6:7]
	s_waitcnt lgkmcnt(0)
	flat_store_dwordx4 v[6:7], v[0:3]
	s_nop 1
	v_add_u32_e32 v0, 0x600, v125
	v_ashrrev_i32_e32 v6, 5, v0
	v_mad_u64_u32 v[0:1], s[6:7], v6, s3, v[4:5]
	ds_read_b128 v[0:3], v0
	v_ashrrev_i32_e32 v7, 31, v6
	v_lshlrev_b64 v[6:7], 12, v[6:7]
	v_lshl_add_u64 v[6:7], v[8:9], 0, v[6:7]
	s_waitcnt lgkmcnt(0)
	flat_store_dwordx4 v[6:7], v[0:3]
	s_nop 1
	v_add_u32_e32 v0, 0x800, v125
	v_ashrrev_i32_e32 v6, 5, v0
	v_mad_u64_u32 v[0:1], s[6:7], v6, s3, v[4:5]
	ds_read_b128 v[0:3], v0
	v_ashrrev_i32_e32 v7, 31, v6
	v_lshlrev_b64 v[6:7], 12, v[6:7]
	v_lshl_add_u64 v[6:7], v[8:9], 0, v[6:7]
	s_waitcnt lgkmcnt(0)
	flat_store_dwordx4 v[6:7], v[0:3]
	s_nop 1
	v_add_u32_e32 v0, 0xa00, v125
	v_ashrrev_i32_e32 v6, 5, v0
	v_mad_u64_u32 v[0:1], s[6:7], v6, s3, v[4:5]
	ds_read_b128 v[0:3], v0
	v_ashrrev_i32_e32 v7, 31, v6
	v_lshlrev_b64 v[6:7], 12, v[6:7]
	v_lshl_add_u64 v[6:7], v[8:9], 0, v[6:7]
	s_waitcnt lgkmcnt(0)
	flat_store_dwordx4 v[6:7], v[0:3]
	s_nop 1
	v_add_u32_e32 v0, 0xc00, v125
	v_ashrrev_i32_e32 v6, 5, v0
	v_mad_u64_u32 v[0:1], s[6:7], v6, s3, v[4:5]
	ds_read_b128 v[0:3], v0
	v_ashrrev_i32_e32 v7, 31, v6
	v_lshlrev_b64 v[6:7], 12, v[6:7]
	v_lshl_add_u64 v[6:7], v[8:9], 0, v[6:7]
	s_waitcnt lgkmcnt(0)
	flat_store_dwordx4 v[6:7], v[0:3]
	s_nop 1
	v_add_u32_e32 v0, 0xe00, v125
	v_ashrrev_i32_e32 v6, 5, v0
	v_mad_u64_u32 v[0:1], s[6:7], v6, s3, v[4:5]
	ds_read_b128 v[0:3], v0
	v_ashrrev_i32_e32 v7, 31, v6
	v_lshlrev_b64 v[6:7], 12, v[6:7]
	v_lshl_add_u64 v[6:7], v[8:9], 0, v[6:7]
	s_waitcnt lgkmcnt(0)
	flat_store_dwordx4 v[6:7], v[0:3]
	s_nop 1
	v_add_u32_e32 v0, 0x1000, v125
	v_ashrrev_i32_e32 v6, 5, v0
	v_mad_u64_u32 v[0:1], s[6:7], v6, s3, v[4:5]
	ds_read_b128 v[0:3], v0
	v_ashrrev_i32_e32 v7, 31, v6
	v_lshlrev_b64 v[6:7], 12, v[6:7]
	v_lshl_add_u64 v[6:7], v[8:9], 0, v[6:7]
	s_waitcnt lgkmcnt(0)
	flat_store_dwordx4 v[6:7], v[0:3]
	s_nop 1
	v_add_u32_e32 v0, 0x1200, v125
	v_ashrrev_i32_e32 v6, 5, v0
	v_mad_u64_u32 v[0:1], s[6:7], v6, s3, v[4:5]
	ds_read_b128 v[0:3], v0
	v_ashrrev_i32_e32 v7, 31, v6
	v_lshlrev_b64 v[6:7], 12, v[6:7]
	v_lshl_add_u64 v[6:7], v[8:9], 0, v[6:7]
	s_waitcnt lgkmcnt(0)
	flat_store_dwordx4 v[6:7], v[0:3]
	s_nop 1
	v_add_u32_e32 v0, 0x1400, v125
	v_ashrrev_i32_e32 v6, 5, v0
	v_mad_u64_u32 v[0:1], s[6:7], v6, s3, v[4:5]
	ds_read_b128 v[0:3], v0
	v_ashrrev_i32_e32 v7, 31, v6
	v_lshlrev_b64 v[6:7], 12, v[6:7]
	v_lshl_add_u64 v[6:7], v[8:9], 0, v[6:7]
	s_waitcnt lgkmcnt(0)
	flat_store_dwordx4 v[6:7], v[0:3]
	s_nop 1
	v_add_u32_e32 v0, 0x1600, v125
	v_ashrrev_i32_e32 v6, 5, v0
	v_mad_u64_u32 v[0:1], s[6:7], v6, s3, v[4:5]
	ds_read_b128 v[0:3], v0
	v_ashrrev_i32_e32 v7, 31, v6
	v_lshlrev_b64 v[6:7], 12, v[6:7]
	v_lshl_add_u64 v[6:7], v[8:9], 0, v[6:7]
	s_waitcnt lgkmcnt(0)
	flat_store_dwordx4 v[6:7], v[0:3]
	s_nop 1
	v_add_u32_e32 v0, 0x1800, v125
	v_ashrrev_i32_e32 v6, 5, v0
	v_mad_u64_u32 v[0:1], s[6:7], v6, s3, v[4:5]
	ds_read_b128 v[0:3], v0
	v_ashrrev_i32_e32 v7, 31, v6
	v_lshlrev_b64 v[6:7], 12, v[6:7]
	v_lshl_add_u64 v[6:7], v[8:9], 0, v[6:7]
	s_waitcnt lgkmcnt(0)
	flat_store_dwordx4 v[6:7], v[0:3]
	s_nop 1
	v_add_u32_e32 v0, 0x1a00, v125
	v_ashrrev_i32_e32 v6, 5, v0
	v_mad_u64_u32 v[0:1], s[6:7], v6, s3, v[4:5]
	ds_read_b128 v[0:3], v0
	v_ashrrev_i32_e32 v7, 31, v6
	v_lshlrev_b64 v[6:7], 12, v[6:7]
	v_lshl_add_u64 v[6:7], v[8:9], 0, v[6:7]
	s_waitcnt lgkmcnt(0)
	flat_store_dwordx4 v[6:7], v[0:3]
	s_nop 1
	v_add_u32_e32 v0, 0x1c00, v125
	v_ashrrev_i32_e32 v6, 5, v0
	v_mad_u64_u32 v[0:1], s[6:7], v6, s3, v[4:5]
	ds_read_b128 v[0:3], v0
	v_ashrrev_i32_e32 v7, 31, v6
	v_lshlrev_b64 v[6:7], 12, v[6:7]
	v_lshl_add_u64 v[6:7], v[8:9], 0, v[6:7]
	s_waitcnt lgkmcnt(0)
	flat_store_dwordx4 v[6:7], v[0:3]
	s_nop 1
	v_add_u32_e32 v0, 0x1e00, v125
	v_ashrrev_i32_e32 v6, 5, v0
	v_mad_u64_u32 v[0:1], s[6:7], v6, s3, v[4:5]
	ds_read_b128 v[0:3], v0
	v_ashrrev_i32_e32 v7, 31, v6
	s_mul_i32 s6, s17, s28
	v_lshlrev_b64 v[4:5], 12, v[6:7]
	s_add_i32 s6, s6, s2
	v_lshl_add_u64 v[4:5], v[8:9], 0, v[4:5]
	s_cmpk_lt_i32 s6, 0xa00
	s_waitcnt lgkmcnt(0)
	flat_store_dwordx4 v[4:5], v[0:3]
	s_waitcnt lgkmcnt(0)
	s_barrier
	s_cbranch_scc1 .LBB0_370

; #define MFMA16(a, b, c) __builtin_amdgcn_mfma_f32_16x16x32_bf16((a), (b), (c), 0, 0, 0)
; DI bf16x8 ldfrag(const char* lds, int row, int chunk) { return *(const bf16x8*)(lds + swz(row, chunk)); }
; #define GEMM_SG1() do { __builtin_amdgcn_sched_group_barrier(0x100, 1, 0); __builtin_amdgcn_sched_group_barrier(0x008, 4, 0); } while (0)
; #define GEMM_SG2() do { __builtin_amdgcn_sched_group_barrier(0x100, 2, 0); __builtin_amdgcn_sched_group_barrier(0x008, 4, 0); } while (0)
; template <bool RSTD, bool SWAP>
; DI void gemm_tile(gacc_t& acc, const bf16_t* __restrict__ A, int lda, const bf16_t* __restrict__ Bt, int ldb, int K,
;                   char* lds, int tid, int wr, int wc, int lane, const float* ssq_row) {
;     ...
;     for (int kt = 0; kt < nk; ++kt) {
;         const char* cur = lds + (kt & 1) * 65536;
;         if (kt + 1 < nk) GEMM_ISSUE(kt + 1, (kt + 1) & 1);
;         bf16x8 bfr[2][4], afr[3];
; #pragma unroll
;         for (int n = 0; n < 4; ++n) bfr[0][n] = ldfrag(cur + 32768, wc * 64 + n * 16 + fr, fq);
;         afr[0] = ldfrag(cur, wr * 128 + fr, fq);
;         afr[1] = ldfrag(cur, wr * 128 + 16 + fr, fq);
; #pragma unroll
;         for (int idx = 0; idx < 16; ++idx) {
;             const int ks = idx >> 3, m = idx & 7;
;             if (idx < 14) afr[(idx + 2) % 3] = ldfrag(cur, wr * 128 + ((idx + 2) & 7) * 16 + fr, ((idx + 2) >> 3) * 4 + fq);
;             if (ks == 0 && m >= 2 && m < 6) bfr[1][m - 2] = ldfrag(cur + 32768, wc * 64 + (m - 2) * 16 + fr, 4 + fq);
; #pragma unroll
;             for (int n = 0; n < 4; ++n) acc[m][n] = SWAP ? MFMA16(bfr[ks][n], afr[idx % 3], acc[m][n]) : MFMA16(afr[idx % 3], bfr[ks][n], acc[m][n]);
;         }
;         __builtin_amdgcn_sched_group_barrier(0x100, 6, 0);
;     ...
;         GEMM_SG1(); GEMM_SG1(); GEMM_SG2(); GEMM_SG2(); GEMM_SG2(); GEMM_SG2(); GEMM_SG1(); GEMM_SG1();
;         GEMM_SG1(); GEMM_SG1(); GEMM_SG1(); GEMM_SG1(); GEMM_SG1(); GEMM_SG1();
;         __builtin_amdgcn_sched_group_barrier(0x008, 8, 0);
;         __builtin_amdgcn_sched_barrier(0);
;         asm volatile("s_waitcnt vmcnt(0)" ::: "memory");
;         __syncthreads();
.LBB0_618:
	s_add_i32 s45, s44, 0xffff0000
	s_and_b32 s45, s45, 0x10000
	s_add_i32 s45, s45, 0
	v_add_u32_e32 v146, s45, v144
	v_add3_u32 v161, v146, v150, v151
	v_add_u32_e32 v166, v146, v148
	ds_read_b128 v[162:165], v161 offset:32768
	ds_read_b128 v[172:175], v161 offset:34816
	ds_read_b128 v[180:183], v161 offset:36864
	ds_read_b128 v[186:189], v161 offset:38912
	ds_read_b128 v[176:179], v166
	ds_read_b128 v[190:193], v166 offset:2048
	v_add_u32_e32 v161, v146, v152
	ds_read_b128 v[194:197], v166 offset:4096
	v_lshl_add_u64 v[240:241], v[140:141], 0, s[12:13]
	v_lshl_add_u64 v[242:243], v[138:139], 0, s[12:13]
	s_and_b32 s48, s44, 0x10000
	s_add_i32 s48, s43, s48
	s_mov_b64 s[46:47], 0x2ee40080
	v_lshl_add_u64 v[232:233], v[240:241], 0, s[46:47]
	s_mov_b32 m0, s48
	v_mfma_f32_16x16x32_bf16 v[60:63], v[198:201], v[214:217], v[60:63]
	global_load_lds_dwordx4 v[232:233], off
	v_mfma_f32_16x16x32_bf16 v[56:59], v[202:205], v[214:217], v[56:59]
	s_mov_b64 s[46:47], 0x1c80080
	v_lshl_add_u64 v[234:235], v[242:243], 0, s[46:47]
	s_add_i32 m0, s48, 0x8000
	v_mfma_f32_16x16x32_bf16 v[52:55], v[206:209], v[214:217], v[52:55]
	global_load_lds_dwordx4 v[234:235], off
	v_mfma_f32_16x16x32_bf16 v[48:51], v[210:213], v[214:217], v[48:51]
	s_mov_b64 s[46:47], 0x2ee60080
	v_lshl_add_u64 v[232:233], v[240:241], 0, s[46:47]
	s_add_i32 m0, s48, 0x2000
	v_mfma_f32_16x16x32_bf16 v[44:47], v[198:201], v[218:221], v[44:47]
	global_load_lds_dwordx4 v[232:233], off
	v_mfma_f32_16x16x32_bf16 v[40:43], v[202:205], v[218:221], v[40:43]
	s_mov_b64 s[46:47], 0x1ca0080
	v_lshl_add_u64 v[234:235], v[242:243], 0, s[46:47]
	s_add_i32 m0, s48, 0xa000
	v_mfma_f32_16x16x32_bf16 v[36:39], v[206:209], v[218:221], v[36:39]
	global_load_lds_dwordx4 v[234:235], off
	v_mfma_f32_16x16x32_bf16 v[32:35], v[210:213], v[218:221], v[32:35]
	s_mov_b64 s[46:47], 0x2ee80080
	v_lshl_add_u64 v[232:233], v[240:241], 0, s[46:47]
	s_add_i32 m0, s48, 0x4000
	v_mfma_f32_16x16x32_bf16 v[28:31], v[198:201], v[222:225], v[28:31]
	global_load_lds_dwordx4 v[232:233], off
	v_mfma_f32_16x16x32_bf16 v[24:27], v[202:205], v[222:225], v[24:27]
	s_mov_b64 s[46:47], 0x1cc0080
	v_lshl_add_u64 v[234:235], v[242:243], 0, s[46:47]
	s_add_i32 m0, s48, 0xc000
	v_mfma_f32_16x16x32_bf16 v[20:23], v[206:209], v[222:225], v[20:23]
	global_load_lds_dwordx4 v[234:235], off
	v_mfma_f32_16x16x32_bf16 v[16:19], v[210:213], v[222:225], v[16:19]
	s_mov_b64 s[46:47], 0x2eea0080
	v_lshl_add_u64 v[232:233], v[240:241], 0, s[46:47]
	s_add_i32 m0, s48, 0x6000
	v_mfma_f32_16x16x32_bf16 v[12:15], v[198:201], v[236:239], v[12:15]
	global_load_lds_dwordx4 v[232:233], off
	v_mfma_f32_16x16x32_bf16 v[8:11], v[202:205], v[236:239], v[8:11]
	s_mov_b64 s[46:47], 0x1ce0080
	v_lshl_add_u64 v[234:235], v[242:243], 0, s[46:47]
	s_add_i32 m0, s48, 0xe000
	v_mfma_f32_16x16x32_bf16 v[4:7], v[206:209], v[236:239], v[4:7]
	global_load_lds_dwordx4 v[234:235], off
	v_mfma_f32_16x16x32_bf16 v[0:3], v[210:213], v[236:239], v[0:3]
	s_waitcnt lgkmcnt(2)
	v_mfma_f32_16x16x32_bf16 v[124:127], v[162:165], v[176:179], v[124:127]
	v_add_u32_e32 v146, v146, v154
	v_mfma_f32_16x16x32_bf16 v[120:123], v[172:175], v[176:179], v[120:123]
	v_mfma_f32_16x16x32_bf16 v[116:119], v[180:183], v[176:179], v[116:119]
	v_mfma_f32_16x16x32_bf16 v[112:115], v[186:189], v[176:179], v[112:115]
	ds_read_b128 v[176:179], v161
	v_add_u32_e32 v161, s45, v149
	v_add_u32_e32 v167, v161, v153
	s_waitcnt lgkmcnt(2)
	v_mfma_f32_16x16x32_bf16 v[108:111], v[162:165], v[190:193], v[108:111]
	v_mfma_f32_16x16x32_bf16 v[104:107], v[172:175], v[190:193], v[104:107]
	v_mfma_f32_16x16x32_bf16 v[100:103], v[180:183], v[190:193], v[100:103]
	v_mfma_f32_16x16x32_bf16 v[96:99], v[186:189], v[190:193], v[96:99]
	ds_read_b128 v[190:193], v166 offset:8192
	ds_read_b128 v[198:201], v167 offset:32768
	s_waitcnt lgkmcnt(3)
	v_mfma_f32_16x16x32_bf16 v[92:95], v[162:165], v[194:197], v[92:95]
	v_mfma_f32_16x16x32_bf16 v[88:91], v[172:175], v[194:197], v[88:91]
	v_mfma_f32_16x16x32_bf16 v[84:87], v[180:183], v[194:197], v[84:87]
	v_mfma_f32_16x16x32_bf16 v[80:83], v[186:189], v[194:197], v[80:83]
	ds_read_b128 v[194:197], v166 offset:10240
	ds_read_b128 v[202:205], v167 offset:34816
	s_waitcnt lgkmcnt(4)
	v_mfma_f32_16x16x32_bf16 v[76:79], v[162:165], v[176:179], v[76:79]
	v_mfma_f32_16x16x32_bf16 v[72:75], v[172:175], v[176:179], v[72:75]
	v_mfma_f32_16x16x32_bf16 v[68:71], v[180:183], v[176:179], v[68:71]
	v_mfma_f32_16x16x32_bf16 v[64:67], v[186:189], v[176:179], v[64:67]
	ds_read_b128 v[176:179], v166 offset:12288
	v_add_u32_e32 v166, v161, v155
	ds_read_b128 v[206:209], v167 offset:36864
	s_waitcnt lgkmcnt(5)
	v_mfma_f32_16x16x32_bf16 v[60:63], v[162:165], v[190:193], v[60:63]
	v_mfma_f32_16x16x32_bf16 v[56:59], v[172:175], v[190:193], v[56:59]
	v_mfma_f32_16x16x32_bf16 v[52:55], v[180:183], v[190:193], v[52:55]
	v_mfma_f32_16x16x32_bf16 v[48:51], v[186:189], v[190:193], v[48:51]
	ds_read_b128 v[210:213], v166 offset:38912
	ds_read_b128 v[190:193], v146
	v_add_u32_e32 v146, v161, v148
	s_waitcnt lgkmcnt(5)
	v_mfma_f32_16x16x32_bf16 v[44:47], v[162:165], v[194:197], v[44:47]
	v_add_u32_e32 v166, v161, v152
	v_mfma_f32_16x16x32_bf16 v[40:43], v[172:175], v[194:197], v[40:43]
	v_mfma_f32_16x16x32_bf16 v[36:39], v[180:183], v[194:197], v[36:39]
	v_mfma_f32_16x16x32_bf16 v[32:35], v[186:189], v[194:197], v[32:35]
	ds_read_b128 v[194:197], v146
	v_add_u32_e32 v230, v161, v154
	s_waitcnt lgkmcnt(4)
	v_mfma_f32_16x16x32_bf16 v[28:31], v[162:165], v[176:179], v[28:31]
	v_mfma_f32_16x16x32_bf16 v[24:27], v[172:175], v[176:179], v[24:27]
	v_mfma_f32_16x16x32_bf16 v[20:23], v[180:183], v[176:179], v[20:23]
	v_mfma_f32_16x16x32_bf16 v[16:19], v[186:189], v[176:179], v[16:19]
	ds_read_b128 v[176:179], v146 offset:2048
	s_waitcnt lgkmcnt(2)
; #define MFMA16(a, b, c) __builtin_amdgcn_mfma_f32_16x16x32_bf16((a), (b), (c), 0, 0, 0)
; DI bf16x8 ldfrag(const char* lds, int row, int chunk) { return *(const bf16x8*)(lds + swz(row, chunk)); }
; #define GEMM_SG1() do { __builtin_amdgcn_sched_group_barrier(0x100, 1, 0); __builtin_amdgcn_sched_group_barrier(0x008, 4, 0); } while (0)
; #define GEMM_SG2() do { __builtin_amdgcn_sched_group_barrier(0x100, 2, 0); __builtin_amdgcn_sched_group_barrier(0x008, 4, 0); } while (0)
; template <bool RSTD, bool SWAP>
; DI void gemm_tile(gacc_t& acc, const bf16_t* __restrict__ A, int lda, const bf16_t* __restrict__ Bt, int ldb, int K,
;                   char* lds, int tid, int wr, int wc, int lane, const float* ssq_row) {
;     ...
;     for (int kt = 0; kt < nk; ++kt) {
;         const char* cur = lds + (kt & 1) * 65536;
;         if (kt + 1 < nk) GEMM_ISSUE(kt + 1, (kt + 1) & 1);
;         bf16x8 bfr[2][4], afr[3];
; #pragma unroll
;         for (int n = 0; n < 4; ++n) bfr[0][n] = ldfrag(cur + 32768, wc * 64 + n * 16 + fr, fq);
;         afr[0] = ldfrag(cur, wr * 128 + fr, fq);
;         afr[1] = ldfrag(cur, wr * 128 + 16 + fr, fq);
; #pragma unroll
;         for (int idx = 0; idx < 16; ++idx) {
;             const int ks = idx >> 3, m = idx & 7;
;             if (idx < 14) afr[(idx + 2) % 3] = ldfrag(cur, wr * 128 + ((idx + 2) & 7) * 16 + fr, ((idx + 2) >> 3) * 4 + fq);
;             if (ks == 0 && m >= 2 && m < 6) bfr[1][m - 2] = ldfrag(cur + 32768, wc * 64 + (m - 2) * 16 + fr, 4 + fq);
; #pragma unroll
;             for (int n = 0; n < 4; ++n) acc[m][n] = SWAP ? MFMA16(bfr[ks][n], afr[idx % 3], acc[m][n]) : MFMA16(afr[idx % 3], bfr[ks][n], acc[m][n]);
;         }
;         __builtin_amdgcn_sched_group_barrier(0x100, 6, 0);
;     ...
;         GEMM_SG1(); GEMM_SG1(); GEMM_SG2(); GEMM_SG2(); GEMM_SG2(); GEMM_SG2(); GEMM_SG1(); GEMM_SG1();
;         GEMM_SG1(); GEMM_SG1(); GEMM_SG1(); GEMM_SG1(); GEMM_SG1(); GEMM_SG1();
;         __builtin_amdgcn_sched_group_barrier(0x008, 8, 0);
;         __builtin_amdgcn_sched_barrier(0);
;         asm volatile("s_waitcnt vmcnt(0)" ::: "memory");
;         __syncthreads();
	v_mfma_f32_16x16x32_bf16 v[12:15], v[162:165], v[190:193], v[12:15]
	v_mfma_f32_16x16x32_bf16 v[8:11], v[172:175], v[190:193], v[8:11]
	v_mfma_f32_16x16x32_bf16 v[4:7], v[180:183], v[190:193], v[4:7]
	v_mfma_f32_16x16x32_bf16 v[0:3], v[186:189], v[190:193], v[0:3]
	ds_read_b128 v[162:165], v146 offset:4096
	s_waitcnt lgkmcnt(2)
	v_mfma_f32_16x16x32_bf16 v[124:127], v[198:201], v[194:197], v[124:127]
	v_mfma_f32_16x16x32_bf16 v[120:123], v[202:205], v[194:197], v[120:123]
	v_mfma_f32_16x16x32_bf16 v[116:119], v[206:209], v[194:197], v[116:119]
	v_mfma_f32_16x16x32_bf16 v[112:115], v[210:213], v[194:197], v[112:115]
	ds_read_b128 v[172:175], v166
	ds_read_b128 v[214:217], v146 offset:8192
	s_waitcnt lgkmcnt(3)
	v_mfma_f32_16x16x32_bf16 v[108:111], v[198:201], v[176:179], v[108:111]
	v_mfma_f32_16x16x32_bf16 v[104:107], v[202:205], v[176:179], v[104:107]
	v_mfma_f32_16x16x32_bf16 v[100:103], v[206:209], v[176:179], v[100:103]
	v_mfma_f32_16x16x32_bf16 v[96:99], v[210:213], v[176:179], v[96:99]
	ds_read_b128 v[218:221], v146 offset:10240
	s_waitcnt lgkmcnt(3)
	v_mfma_f32_16x16x32_bf16 v[92:95], v[198:201], v[162:165], v[92:95]
	v_mfma_f32_16x16x32_bf16 v[88:91], v[202:205], v[162:165], v[88:91]
	v_mfma_f32_16x16x32_bf16 v[84:87], v[206:209], v[162:165], v[84:87]
	v_mfma_f32_16x16x32_bf16 v[80:83], v[210:213], v[162:165], v[80:83]
	ds_read_b128 v[222:225], v146 offset:12288
	ds_read_b128 v[236:239], v230
	s_waitcnt lgkmcnt(4)
	v_mfma_f32_16x16x32_bf16 v[76:79], v[198:201], v[172:175], v[76:79]
	v_mfma_f32_16x16x32_bf16 v[72:75], v[202:205], v[172:175], v[72:75]
	v_mfma_f32_16x16x32_bf16 v[68:71], v[206:209], v[172:175], v[68:71]
	v_mfma_f32_16x16x32_bf16 v[64:67], v[210:213], v[172:175], v[64:67]
	s_waitcnt lgkmcnt(0)
	s_waitcnt vmcnt(0)
	s_add_u32 s12, s12, 0x80
	s_addc_u32 s13, s13, 0
	s_add_i32 s44, s44, 0x10000
	s_cmpk_lg_i32 s12, 0x780
	s_waitcnt vmcnt(0)
	s_cbranch_scc1 .Lkhead_618
	s_barrier
	v_mfma_f32_16x16x32_bf16 v[60:63], v[198:201], v[214:217], v[60:63]
	v_mfma_f32_16x16x32_bf16 v[56:59], v[202:205], v[214:217], v[56:59]
	v_mfma_f32_16x16x32_bf16 v[52:55], v[206:209], v[214:217], v[52:55]
	v_mfma_f32_16x16x32_bf16 v[48:51], v[210:213], v[214:217], v[48:51]
	v_mfma_f32_16x16x32_bf16 v[44:47], v[198:201], v[218:221], v[44:47]
	v_mfma_f32_16x16x32_bf16 v[40:43], v[202:205], v[218:221], v[40:43]
	v_mfma_f32_16x16x32_bf16 v[36:39], v[206:209], v[218:221], v[36:39]
	v_mfma_f32_16x16x32_bf16 v[32:35], v[210:213], v[218:221], v[32:35]
	v_mfma_f32_16x16x32_bf16 v[28:31], v[198:201], v[222:225], v[28:31]
	v_mfma_f32_16x16x32_bf16 v[24:27], v[202:205], v[222:225], v[24:27]
	v_mfma_f32_16x16x32_bf16 v[20:23], v[206:209], v[222:225], v[20:23]
	v_mfma_f32_16x16x32_bf16 v[16:19], v[210:213], v[222:225], v[16:19]
	v_mfma_f32_16x16x32_bf16 v[12:15], v[198:201], v[236:239], v[12:15]
	v_mfma_f32_16x16x32_bf16 v[8:11], v[202:205], v[236:239], v[8:11]
	v_mfma_f32_16x16x32_bf16 v[4:7], v[206:209], v[236:239], v[4:7]
	v_mfma_f32_16x16x32_bf16 v[0:3], v[210:213], v[236:239], v[0:3]
	ds_read_b128 v[138:141], v160
	ds_read_b128 v[162:165], v160 offset:2048
	ds_read_b128 v[176:179], v160 offset:4096
	ds_read_b128 v[180:183], v160 offset:6144
	v_add_u32_e32 v146, v156, v148
	ds_read_b128 v[172:175], v146
	ds_read_b128 v[186:189], v146 offset:2048
	v_add_u32_e32 v161, v156, v152
	ds_read_b128 v[190:193], v146 offset:4096
	s_waitcnt lgkmcnt(2)
	v_mfma_f32_16x16x32_bf16 v[124:127], v[138:141], v[172:175], v[124:127]
	v_mfma_f32_16x16x32_bf16 v[120:123], v[162:165], v[172:175], v[120:123]
	v_mfma_f32_16x16x32_bf16 v[116:119], v[176:179], v[172:175], v[116:119]
	v_mfma_f32_16x16x32_bf16 v[112:115], v[180:183], v[172:175], v[112:115]
	ds_read_b128 v[172:175], v161
	v_add_u32_e32 v161, v157, v153
	s_waitcnt lgkmcnt(2)
	v_mfma_f32_16x16x32_bf16 v[108:111], v[138:141], v[186:189], v[108:111]
	v_mfma_f32_16x16x32_bf16 v[104:107], v[162:165], v[186:189], v[104:107]
	v_mfma_f32_16x16x32_bf16 v[100:103], v[176:179], v[186:189], v[100:103]
	v_mfma_f32_16x16x32_bf16 v[96:99], v[180:183], v[186:189], v[96:99]
	ds_read_b128 v[186:189], v146 offset:8192
	ds_read_b128 v[194:197], v161
	s_waitcnt lgkmcnt(3)
	v_mfma_f32_16x16x32_bf16 v[92:95], v[138:141], v[190:193], v[92:95]
	v_mfma_f32_16x16x32_bf16 v[88:91], v[162:165], v[190:193], v[88:91]
	v_mfma_f32_16x16x32_bf16 v[84:87], v[176:179], v[190:193], v[84:87]
	v_mfma_f32_16x16x32_bf16 v[80:83], v[180:183], v[190:193], v[80:83]
	ds_read_b128 v[190:193], v146 offset:10240
	ds_read_b128 v[198:201], v161 offset:2048
	s_waitcnt lgkmcnt(4)
	v_mfma_f32_16x16x32_bf16 v[76:79], v[138:141], v[172:175], v[76:79]
	v_mfma_f32_16x16x32_bf16 v[72:75], v[162:165], v[172:175], v[72:75]
	v_mfma_f32_16x16x32_bf16 v[68:71], v[176:179], v[172:175], v[68:71]
	v_mfma_f32_16x16x32_bf16 v[64:67], v[180:183], v[172:175], v[64:67]
	ds_read_b128 v[172:175], v146 offset:12288
	v_add_u32_e32 v146, v156, v154
	ds_read_b128 v[202:205], v161 offset:4096
	s_waitcnt lgkmcnt(5)
	v_mfma_f32_16x16x32_bf16 v[60:63], v[138:141], v[186:189], v[60:63]
	v_mfma_f32_16x16x32_bf16 v[56:59], v[162:165], v[186:189], v[56:59]
	v_mfma_f32_16x16x32_bf16 v[52:55], v[176:179], v[186:189], v[52:55]
	v_mfma_f32_16x16x32_bf16 v[48:51], v[180:183], v[186:189], v[48:51]
	ds_read_b128 v[186:189], v146
	v_add_u32_e32 v146, v157, v155
	ds_read_b128 v[206:209], v146 offset:6144
	v_add_u32_e32 v146, v158, v148
	s_waitcnt lgkmcnt(5)
; #define MFMA16(a, b, c) __builtin_amdgcn_mfma_f32_16x16x32_bf16((a), (b), (c), 0, 0, 0)
; DI unsigned pk2(float a, float b) { f32x2 v = {a, b}; bf16x2_t r = __builtin_convertvector(v, bf16x2_t); return __builtin_bit_cast(unsigned, r); }
; DI bf16x8 ldfrag(const char* lds, int row, int chunk) { return *(const bf16x8*)(lds + swz(row, chunk)); }
; template <bool RSTD, bool SWAP>
; DI void gemm_tile(gacc_t& acc, const bf16_t* __restrict__ A, int lda, const bf16_t* __restrict__ Bt, int ldb, int K,
;                   char* lds, int tid, int wr, int wc, int lane, const float* ssq_row) {
;     ...
;         for (int idx = 0; idx < 16; ++idx) {
;             const int ks = idx >> 3, m = idx & 7;
;             if (idx < 14) afr[(idx + 2) % 3] = ldfrag(cur, wr * 128 + ((idx + 2) & 7) * 16 + fr, ((idx + 2) >> 3) * 4 + fq);
;             if (ks == 0 && m >= 2 && m < 6) bfr[1][m - 2] = ldfrag(cur + 32768, wc * 64 + (m - 2) * 16 + fr, 4 + fq);
; #pragma unroll
;             for (int n = 0; n < 4; ++n) acc[m][n] = SWAP ? MFMA16(bfr[ks][n], afr[idx % 3], acc[m][n]) : MFMA16(afr[idx % 3], bfr[ks][n], acc[m][n]);
;     DI void operator()(gacc_t& acc, int pm, int pn, char* lds, int tid, int wr, int wc, int lane) const {
;     ...
;             char* lbase = lds + (wr * 128 + fr) * RS + (wc * 64 + 4 * fq) * 2;
;             bf16_t* hrow = halo + (long)(pm * 4) * 5632 + pn * 256 + wc * 64 + 4 * fq;
; #pragma unroll
;             for (int m = 0; m < 8; ++m) {
;                 const float r = rl[m * 16];
; #pragma unroll
;                 for (int n = 0; n < 4; ++n) {
;                     u32x2 w; w.x = pk2(acc[m][n][0] * r, acc[m][n][1] * r); w.y = pk2(acc[m][n][2] * r, acc[m][n][3] * r);
;                     *(u32x2*)(lbase + m * 16 * RS + n * 32) = w;
;                     if (m == 0 && wr == 0 && fr < 2) *(u32x2*)(hrow + fr * 5632 + n * 16) = w;
;                     if (m == 7 && wr == 1 && fr >= 14) *(u32x2*)(hrow + (fr - 12) * 5632 + n * 16) = w;
	v_mfma_f32_16x16x32_bf16 v[44:47], v[138:141], v[190:193], v[44:47]
	v_mfma_f32_16x16x32_bf16 v[40:43], v[162:165], v[190:193], v[40:43]
	v_mfma_f32_16x16x32_bf16 v[36:39], v[176:179], v[190:193], v[36:39]
	v_mfma_f32_16x16x32_bf16 v[32:35], v[180:183], v[190:193], v[32:35]
	ds_read_b128 v[190:193], v146
	s_waitcnt lgkmcnt(4)
	v_mfma_f32_16x16x32_bf16 v[28:31], v[138:141], v[172:175], v[28:31]
	v_mfma_f32_16x16x32_bf16 v[24:27], v[162:165], v[172:175], v[24:27]
	v_mfma_f32_16x16x32_bf16 v[20:23], v[176:179], v[172:175], v[20:23]
	v_mfma_f32_16x16x32_bf16 v[16:19], v[180:183], v[172:175], v[16:19]
	ds_read_b128 v[172:175], v146 offset:2048
	s_waitcnt lgkmcnt(3)
	v_mfma_f32_16x16x32_bf16 v[12:15], v[138:141], v[186:189], v[12:15]
	v_mfma_f32_16x16x32_bf16 v[8:11], v[162:165], v[186:189], v[8:11]
	v_mfma_f32_16x16x32_bf16 v[4:7], v[176:179], v[186:189], v[4:7]
	v_mfma_f32_16x16x32_bf16 v[138:141], v[180:183], v[186:189], v[0:3]
	s_nop 2
	ds_read_b128 v[0:3], v146 offset:4096
	s_waitcnt lgkmcnt(2)
	v_mfma_f32_16x16x32_bf16 v[164:167], v[194:197], v[190:193], v[124:127]
	v_mfma_f32_16x16x32_bf16 v[120:123], v[198:201], v[190:193], v[120:123]
	s_nop 1
	v_add_u32_e32 v124, v158, v152
	v_mfma_f32_16x16x32_bf16 v[116:119], v[202:205], v[190:193], v[116:119]
	v_mfma_f32_16x16x32_bf16 v[112:115], v[206:209], v[190:193], v[112:115]
	ds_read_b128 v[124:127], v124
	s_waitcnt lgkmcnt(2)
	v_mfma_f32_16x16x32_bf16 v[108:111], v[194:197], v[172:175], v[108:111]
	v_mfma_f32_16x16x32_bf16 v[104:107], v[198:201], v[172:175], v[104:107]
	v_mfma_f32_16x16x32_bf16 v[100:103], v[202:205], v[172:175], v[100:103]
	v_mfma_f32_16x16x32_bf16 v[96:99], v[206:209], v[172:175], v[96:99]
	ds_read_b128 v[172:175], v146 offset:8192
	s_waitcnt lgkmcnt(2)
	v_mfma_f32_16x16x32_bf16 v[92:95], v[194:197], v[0:3], v[92:95]
	v_mfma_f32_16x16x32_bf16 v[88:91], v[198:201], v[0:3], v[88:91]
	v_mfma_f32_16x16x32_bf16 v[84:87], v[202:205], v[0:3], v[84:87]
	v_mfma_f32_16x16x32_bf16 v[80:83], v[206:209], v[0:3], v[80:83]
	ds_read_b128 v[0:3], v146 offset:10240
	s_waitcnt lgkmcnt(2)
	v_mfma_f32_16x16x32_bf16 v[76:79], v[194:197], v[124:127], v[76:79]
	v_mfma_f32_16x16x32_bf16 v[72:75], v[198:201], v[124:127], v[72:75]
	v_mfma_f32_16x16x32_bf16 v[68:71], v[202:205], v[124:127], v[68:71]
	v_mfma_f32_16x16x32_bf16 v[64:67], v[206:209], v[124:127], v[64:67]
	ds_read_b128 v[124:127], v146 offset:12288
	v_add_u32_e32 v146, v158, v154
	s_waitcnt lgkmcnt(2)
	v_mfma_f32_16x16x32_bf16 v[60:63], v[194:197], v[172:175], v[60:63]
	v_mfma_f32_16x16x32_bf16 v[56:59], v[198:201], v[172:175], v[56:59]
	v_mfma_f32_16x16x32_bf16 v[52:55], v[202:205], v[172:175], v[52:55]
	v_mfma_f32_16x16x32_bf16 v[48:51], v[206:209], v[172:175], v[48:51]
	ds_read_b128 v[172:175], v146
	s_waitcnt lgkmcnt(2)
	v_mfma_f32_16x16x32_bf16 v[44:47], v[194:197], v[0:3], v[44:47]
	v_mfma_f32_16x16x32_bf16 v[40:43], v[198:201], v[0:3], v[40:43]
	v_mfma_f32_16x16x32_bf16 v[36:39], v[202:205], v[0:3], v[36:39]
	v_mfma_f32_16x16x32_bf16 v[32:35], v[206:209], v[0:3], v[32:35]
	s_waitcnt lgkmcnt(1)
	v_mfma_f32_16x16x32_bf16 v[28:31], v[194:197], v[124:127], v[28:31]
	v_mfma_f32_16x16x32_bf16 v[24:27], v[198:201], v[124:127], v[24:27]
	v_mfma_f32_16x16x32_bf16 v[20:23], v[202:205], v[124:127], v[20:23]
	v_mfma_f32_16x16x32_bf16 v[16:19], v[206:209], v[124:127], v[16:19]
	s_waitcnt lgkmcnt(0)
	v_mfma_f32_16x16x32_bf16 v[12:15], v[194:197], v[172:175], v[12:15]
	v_mfma_f32_16x16x32_bf16 v[8:11], v[198:201], v[172:175], v[8:11]
	v_mfma_f32_16x16x32_bf16 v[0:3], v[202:205], v[172:175], v[4:7]
	v_mfma_f32_16x16x32_bf16 v[4:7], v[206:209], v[172:175], v[138:141]
	s_lshl_b32 s12, s42, 2
	s_mul_i32 s13, s42, 0xb000
	s_mul_hi_i32 s12, s12, 0x2c00
	s_add_u32 s43, s22, s13
	v_mov_b32_e32 v124, v142
	v_mov_b32_e32 v140, v133
	s_addc_u32 s44, s23, s12
	s_lshl_b32 s12, s40, 8
	s_waitcnt vmcnt(0)
	s_barrier
	s_ashr_i32 s13, s12, 31
	v_and_b32_e32 v162, 15, v124
	v_or_b32_e32 v125, v162, v145
	v_ashrrev_i32_e32 v124, 2, v124
	s_lshl_b64 s[12:13], s[12:13], 1
	v_mul_lo_u32 v125, v125, s3
	v_and_b32_e32 v124, -4, v124
	s_add_u32 s12, s43, s12
	v_add_u32_e32 v125, 0, v125
	v_add_lshl_u32 v126, v124, v132, 1
	s_addc_u32 s13, s44, s13
	v_lshlrev_b32_e32 v146, 1, v132
	v_lshl_add_u32 v161, v162, 2, v159
	v_add_u32_e32 v141, v125, v126
	v_lshl_add_u64 v[126:127], s[12:13], 0, v[146:147]
	v_ashrrev_i32_e32 v125, 31, v124
	v_lshl_add_u64 v[124:125], v[124:125], 1, v[126:127]
	ds_read_b32 v244, v161
	ds_read_b32 v245, v161 offset:64
	ds_read_b32 v246, v161 offset:128
	ds_read_b32 v247, v161 offset:192
	ds_read_b32 v248, v161 offset:256
	ds_read_b32 v249, v161 offset:320
	ds_read_b32 v250, v161 offset:384
	ds_read_b32 v251, v161 offset:448
	v_mul_u32_u24_e32 v127, 0x1600, v162
	v_cmp_gt_u32_e32 vcc, 2, v162
	v_lshlrev_b32_e32 v146, 1, v127
	v_lshl_add_u64 v[124:125], v[124:125], 0, v[146:147]
	s_waitcnt lgkmcnt(0)
	v_mov_b32_e32 v126, v244
	v_pk_mul_f32 v[138:139], v[164:165], v[126:127] op_sel_hi:[1,0]
	v_pk_mul_f32 v[164:165], v[166:167], v[126:127] op_sel_hi:[1,0]
	s_and_b64 s[12:13], s[8:9], vcc
	v_cvt_pk_bf16_f32 v138, v138, v139
	v_cvt_pk_bf16_f32 v139, v164, v165
	ds_write_b64 v141, v[138:139]
	s_and_saveexec_b64 s[44:45], s[12:13]
	s_cbranch_execz .LBB0_621
	flat_store_dwordx2 v[124:125], v[138:139]
